# conv: shifted-weight copy and (bias, 0) pair set up once before the unit loop
# baseline (speedup 1.0000x reference)
.LBB0_438:
	s_lshl_b32 s0, s2, 7
	s_and_b32 s0, s0, 0x380
	s_ashr_i32 s4, s2, 3
	s_add_i32 s43, s0, s4
	s_add_i32 s0, 0, 0x10000
	v_lshl_add_u32 v35, v65, 2, s0
	v_mbcnt_hi_u32_b32 v65, -1, v243
	v_and_b32_e32 v101, 64, v65
	v_add_u32_e32 v106, 64, v101
	v_xor_b32_e32 v101, 1, v65
	v_cmp_lt_i32_e32 vcc, v101, v106
	v_xor_b32_e32 v102, 2, v65
	v_xor_b32_e32 v103, 4, v65
	v_cndmask_b32_e32 v101, v65, v101, vcc
	v_cmp_lt_i32_e32 vcc, v102, v106
	v_xor_b32_e32 v104, 8, v65
	v_xor_b32_e32 v105, 16, v65
	v_cndmask_b32_e32 v102, v65, v102, vcc
	v_cmp_lt_i32_e32 vcc, v103, v106
	v_xor_b32_e32 v107, 32, v65
	v_add_u32_e32 v33, 0, v62
	v_cndmask_b32_e32 v103, v65, v103, vcc
	v_cmp_lt_i32_e32 vcc, v104, v106
	v_and_b32_e32 v55, 0x7ffffe00, v55
	v_lshl_add_u32 v100, v172, 2, s0
	v_cndmask_b32_e32 v104, v65, v104, vcc
	v_cmp_lt_i32_e32 vcc, v105, v106
	s_movk_i32 s0, 0xf80
	v_mov_b32_e32 v32, 0
	v_cndmask_b32_e32 v105, v65, v105, vcc
	v_cmp_lt_i32_e32 vcc, v107, v106
	v_cmp_gt_i32_e64 s[4:5], s0, v172
	s_movk_i32 s0, 0xd80
	v_cndmask_b32_e32 v65, v65, v107, vcc
	v_lshl_add_u32 v107, v55, 1, v33
	v_lshlrev_b32_e32 v55, 4, v56
	v_and_b32_e32 v55, 0xfffffc00, v55
	v_add_u32_e32 v108, v33, v55
	v_lshlrev_b32_e32 v55, 4, v57
	v_and_b32_e32 v55, 0xfffffc00, v55
	v_add_u32_e32 v109, v33, v55
	v_lshlrev_b32_e32 v55, 4, v58
	v_and_b32_e32 v55, 0xfffffc00, v55
	v_add_u32_e32 v110, v33, v55
	v_lshlrev_b32_e32 v55, 4, v59
	v_and_b32_e32 v55, 0xfffffc00, v55
	v_add_u32_e32 v111, v33, v55
	v_lshlrev_b32_e32 v55, 4, v60
	v_and_b32_e32 v55, 0xfffffc00, v55
	v_mov_b32_e32 v63, v32
	v_cmp_gt_i32_e64 s[6:7], s0, v172
	s_movk_i32 s0, 0xb80
	v_add_u32_e32 v112, v33, v55
	v_lshlrev_b32_e32 v55, 4, v61
	v_lshl_add_u64 v[52:53], s[8:9], 0, v[62:63]
	v_ashrrev_i32_e32 v34, 4, v172
	v_cmp_gt_i32_e64 s[8:9], s0, v172
	s_movk_i32 s0, 0x980
	v_and_b32_e32 v55, 0xfffffc00, v55
	v_and_b32_e32 v54, -4, v34
	v_cmp_gt_i32_e64 s[10:11], s0, v172
	s_movk_i32 s0, 0x780
	v_add_u32_e32 v113, v33, v55
	v_lshlrev_b32_e32 v55, 4, v64
	v_cmp_gt_i32_e64 s[12:13], s0, v172
	s_movk_i32 s0, 0x580
	v_and_b32_e32 v55, 0xfffffc00, v55
	v_ashrrev_i32_e32 v115, 6, v56
	v_ashrrev_i32_e32 v117, 6, v58
	v_ashrrev_i32_e32 v119, 6, v60
	v_or_b32_e32 v56, 1, v54
	v_or_b32_e32 v58, 2, v54
	v_or_b32_e32 v60, 3, v34
	s_movk_i32 s1, 0x380
	v_lshlrev_b32_e32 v106, 2, v65
	v_cmp_gt_i32_e64 s[14:15], s0, v172
	s_movk_i32 s0, 0x180
	v_add_u32_e32 v114, v33, v55
	v_ashrrev_i32_e32 v121, 6, v64
	v_lshlrev_b32_e32 v33, 11, v54
	v_lshlrev_b32_e32 v64, 11, v56
	v_lshlrev_b32_e32 v65, 11, v58
	v_lshlrev_b32_e32 v34, 11, v60
	s_mov_b32 s44, 0
	v_lshl_add_u32 v99, v172, 1, 0
	v_lshlrev_b32_e32 v101, 2, v101
	v_lshlrev_b32_e32 v102, 2, v102
	v_lshlrev_b32_e32 v103, 2, v103
	v_lshlrev_b32_e32 v104, 2, v104
	v_lshlrev_b32_e32 v105, 2, v105
	v_cmp_gt_i32_e64 s[16:17], s1, v172
	v_cmp_gt_i32_e64 s[18:19], s0, v172
	v_ashrrev_i32_e32 v116, 6, v57
	v_ashrrev_i32_e32 v118, 6, v59
	v_ashrrev_i32_e32 v120, 6, v61
	v_ashrrev_i32_e32 v55, 31, v54
	v_ashrrev_i32_e32 v57, 31, v56
	v_ashrrev_i32_e32 v59, 31, v58
	v_ashrrev_i32_e32 v61, 31, v60
	v_lshl_add_u64 v[62:63], s[36:37], 0, v[62:63]
	v_add_u32_e32 v122, v35, v33
	v_mov_b32_e32 v123, 0x358637bd
	s_mov_b32 s45, 0xf800000
	v_mov_b32_e32 v124, 0x260
	s_movk_i32 s52, 0x7fff
	s_mov_b32 s53, 0xffff0000
	v_add_u32_e32 v125, v35, v64
	v_add_u32_e32 v126, v35, v65
	v_add_u32_e32 v127, v35, v34
	s_waitcnt vmcnt(0)
	v_mov_b32_e32 v200, v67
	v_mov_b32_e32 v201, v68
	v_mov_b32_e32 v202, v69
	v_mov_b32_e32 v203, v70
	v_mov_b32_e32 v204, v71
	v_mov_b32_e32 v205, v72
	v_mov_b32_e32 v206, v73
	v_mov_b32_e32 v207, v74
	v_mov_b32_e32 v208, v75
	v_mov_b32_e32 v209, v76
	v_mov_b32_e32 v210, v77
	v_mov_b32_e32 v211, v78
	v_mov_b32_e32 v212, v79
	v_mov_b32_e32 v213, v80
	v_mov_b32_e32 v214, v81
	v_mov_b32_e32 v215, v82
	v_mov_b32_e32 v216, v83
	v_mov_b32_e32 v217, v84
	v_mov_b32_e32 v218, v85
	v_mov_b32_e32 v219, v86
	v_mov_b32_e32 v220, v87
	v_mov_b32_e32 v221, v88
	v_mov_b32_e32 v222, v89
	v_mov_b32_e32 v223, v90
	v_mov_b32_e32 v224, v91
	v_mov_b32_e32 v225, v92
	v_mov_b32_e32 v226, v93
	v_mov_b32_e32 v227, v94
	v_mov_b32_e32 v228, v95
	v_mov_b32_e32 v229, v96
	v_mov_b32_e32 v230, v97
	v_mov_b32_e32 v231, 0
	s_branch .LBB0_441

.LBB0_440:
	ds_read_u16 v128, v99
	ds_read_u16 v129, v99 offset:1024
	ds_read_u16 v130, v99 offset:2048
	ds_read_u16 v131, v99 offset:3072
	ds_read_u16 v132, v99 offset:4096
	ds_read_u16 v133, v99 offset:5120
	ds_read_u16 v134, v99 offset:6144
	ds_read_u16 v135, v99 offset:7168
	ds_read_u16 v136, v99 offset:8192
	ds_read_u16 v137, v99 offset:9216
	ds_read_u16 v138, v99 offset:10240
	ds_read_u16 v139, v99 offset:11264
	ds_read_u16 v140, v99 offset:12288
	ds_read_u16 v141, v99 offset:13312
	s_waitcnt lgkmcnt(7)
	v_lshlrev_b32_e32 v128, 16, v128
	v_lshlrev_b32_e32 v129, 16, v129
	v_lshlrev_b32_e32 v130, 16, v130
	v_lshlrev_b32_e32 v131, 16, v131
	v_lshlrev_b32_e32 v132, 16, v132
	v_lshlrev_b32_e32 v133, 16, v133
	v_lshlrev_b32_e32 v134, 16, v134
	ds_read_u16 v142, v99 offset:14336
	ds_read_u16 v143, v99 offset:15360
	ds_read_u16 v144, v99 offset:16384
	ds_read_u16 v145, v99 offset:17408
	ds_read_u16 v146, v99 offset:18432
	ds_read_u16 v147, v99 offset:19456
	ds_read_u16 v148, v99 offset:20480
	s_waitcnt lgkmcnt(7)
	v_lshlrev_b32_e32 v135, 16, v135
	v_lshlrev_b32_e32 v136, 16, v136
	v_lshlrev_b32_e32 v137, 16, v137
	v_lshlrev_b32_e32 v138, 16, v138
	v_lshlrev_b32_e32 v139, 16, v139
	v_lshlrev_b32_e32 v140, 16, v140
	v_lshlrev_b32_e32 v141, 16, v141
	ds_read_u16 v149, v99 offset:21504
	ds_read_u16 v150, v99 offset:22528
	ds_read_u16 v151, v99 offset:23552
	ds_read_u16 v152, v99 offset:24576
	ds_read_u16 v153, v99 offset:25600
	ds_read_u16 v154, v99 offset:26624
	ds_read_u16 v155, v99 offset:27648
	s_waitcnt lgkmcnt(7)
	v_lshlrev_b32_e32 v142, 16, v142
	v_lshlrev_b32_e32 v143, 16, v143
	v_lshlrev_b32_e32 v144, 16, v144
	v_lshlrev_b32_e32 v145, 16, v145
	v_lshlrev_b32_e32 v146, 16, v146
	v_lshlrev_b32_e32 v147, 16, v147
	v_lshlrev_b32_e32 v148, 16, v148
	ds_read_u16 v156, v99 offset:28672
	ds_read_u16 v157, v99 offset:29696
	ds_read_u16 v158, v99 offset:30720
	ds_read_u16 v159, v99 offset:31744
	ds_read_u16 v160, v99 offset:32768
	ds_read_u16 v161, v99 offset:33792
	ds_read_u16 v162, v99 offset:34816
	s_waitcnt lgkmcnt(7)
	v_lshlrev_b32_e32 v149, 16, v149
	v_lshlrev_b32_e32 v150, 16, v150
	v_lshlrev_b32_e32 v151, 16, v151
	v_lshlrev_b32_e32 v152, 16, v152
	v_lshlrev_b32_e32 v153, 16, v153
	v_lshlrev_b32_e32 v154, 16, v154
	v_lshlrev_b32_e32 v155, 16, v155
	ds_read_u16 v163, v99 offset:35840
	ds_read_u16 v164, v99 offset:36864
	ds_read_u16 v165, v99 offset:37888
	ds_read_u16 v166, v99 offset:38912
	ds_read_u16 v167, v99 offset:39936
	ds_read_u16 v168, v99 offset:40960
	ds_read_u16 v169, v99 offset:41984
	s_waitcnt lgkmcnt(7)
	v_lshlrev_b32_e32 v156, 16, v156
	v_lshlrev_b32_e32 v157, 16, v157
	v_lshlrev_b32_e32 v158, 16, v158
	v_lshlrev_b32_e32 v159, 16, v159
	v_lshlrev_b32_e32 v160, 16, v160
	v_lshlrev_b32_e32 v161, 16, v161
	v_lshlrev_b32_e32 v162, 16, v162
	ds_read_u16 v170, v99 offset:43008
	ds_read_u16 v171, v99 offset:44032
	ds_read_u16 v174, v99 offset:45056
	ds_read_u16 v175, v99 offset:46080
	ds_read_u16 v176, v99 offset:47104
	ds_read_u16 v177, v99 offset:48128
	ds_read_u16 v178, v99 offset:49152
	s_waitcnt lgkmcnt(7)
	v_lshlrev_b32_e32 v163, 16, v163
	v_lshlrev_b32_e32 v164, 16, v164
	v_lshlrev_b32_e32 v165, 16, v165
	v_lshlrev_b32_e32 v166, 16, v166
	v_lshlrev_b32_e32 v167, 16, v167
	v_lshlrev_b32_e32 v168, 16, v168
	v_lshlrev_b32_e32 v169, 16, v169
	ds_read_u16 v179, v99 offset:50176
	ds_read_u16 v180, v99 offset:51200
	ds_read_u16 v181, v99 offset:52224
	ds_read_u16 v182, v99 offset:53248
	ds_read_u16 v183, v99 offset:54272
	ds_read_u16 v184, v99 offset:55296
	ds_read_u16 v185, v99 offset:56320
	s_waitcnt lgkmcnt(7)
	v_lshlrev_b32_e32 v170, 16, v170
	v_lshlrev_b32_e32 v171, 16, v171
	v_lshlrev_b32_e32 v174, 16, v174
	v_lshlrev_b32_e32 v175, 16, v175
	v_lshlrev_b32_e32 v176, 16, v176
	v_lshlrev_b32_e32 v177, 16, v177
	v_lshlrev_b32_e32 v178, 16, v178
	ds_read_u16 v186, v99 offset:57344
	ds_read_u16 v187, v99 offset:58368
	ds_read_u16 v188, v99 offset:59392
	ds_read_u16 v189, v99 offset:60416
	ds_read_u16 v190, v99 offset:61440
	ds_read_u16 v191, v99 offset:62464
	s_waitcnt lgkmcnt(6)
	v_lshlrev_b32_e32 v179, 16, v179
	v_lshlrev_b32_e32 v180, 16, v180
	v_lshlrev_b32_e32 v181, 16, v181
	v_lshlrev_b32_e32 v182, 16, v182
	v_lshlrev_b32_e32 v183, 16, v183
	v_lshlrev_b32_e32 v184, 16, v184
	v_lshlrev_b32_e32 v185, 16, v185
	s_waitcnt lgkmcnt(0)
	v_lshlrev_b32_e32 v186, 16, v186
	v_lshlrev_b32_e32 v187, 16, v187
	v_lshlrev_b32_e32 v188, 16, v188
	v_lshlrev_b32_e32 v189, 16, v189
	v_lshlrev_b32_e32 v190, 16, v190
	v_lshlrev_b32_e32 v191, 16, v191
	v_pk_fma_f32 v[192:193], v[66:67], v[128:129], v[230:231]
	v_pk_fma_f32 v[192:193], v[68:69], v[130:131], v[192:193]
	v_pk_fma_f32 v[192:193], v[70:71], v[132:133], v[192:193]
	v_pk_fma_f32 v[192:193], v[72:73], v[134:135], v[192:193]
	v_pk_fma_f32 v[192:193], v[74:75], v[136:137], v[192:193]
	v_pk_fma_f32 v[192:193], v[76:77], v[138:139], v[192:193]
	v_pk_fma_f32 v[192:193], v[78:79], v[140:141], v[192:193]
	v_pk_fma_f32 v[192:193], v[80:81], v[142:143], v[192:193]
	v_pk_fma_f32 v[192:193], v[82:83], v[144:145], v[192:193]
	v_pk_fma_f32 v[192:193], v[84:85], v[146:147], v[192:193]
	v_pk_fma_f32 v[192:193], v[86:87], v[148:149], v[192:193]
	v_pk_fma_f32 v[192:193], v[88:89], v[150:151], v[192:193]
	v_pk_fma_f32 v[192:193], v[90:91], v[152:153], v[192:193]
	v_pk_fma_f32 v[192:193], v[92:93], v[154:155], v[192:193]
	v_pk_fma_f32 v[192:193], v[94:95], v[156:157], v[192:193]
	v_fmac_f32_e32 v192, v96, v158
	v_add_f32_e32 v232, v193, v192
	v_fma_f32 v195, v66, v129, v97
	v_mov_b32_e32 v194, 0
	v_pk_fma_f32 v[194:195], v[200:201], v[130:131], v[194:195]
	v_pk_fma_f32 v[194:195], v[202:203], v[132:133], v[194:195]
	v_pk_fma_f32 v[194:195], v[204:205], v[134:135], v[194:195]
	v_pk_fma_f32 v[194:195], v[206:207], v[136:137], v[194:195]
	v_pk_fma_f32 v[194:195], v[208:209], v[138:139], v[194:195]
	v_pk_fma_f32 v[194:195], v[210:211], v[140:141], v[194:195]
	v_pk_fma_f32 v[194:195], v[212:213], v[142:143], v[194:195]
	v_pk_fma_f32 v[194:195], v[214:215], v[144:145], v[194:195]
	v_pk_fma_f32 v[194:195], v[216:217], v[146:147], v[194:195]
	v_pk_fma_f32 v[194:195], v[218:219], v[148:149], v[194:195]
	v_pk_fma_f32 v[194:195], v[220:221], v[150:151], v[194:195]
	v_pk_fma_f32 v[194:195], v[222:223], v[152:153], v[194:195]
	v_pk_fma_f32 v[194:195], v[224:225], v[154:155], v[194:195]
	v_pk_fma_f32 v[194:195], v[226:227], v[156:157], v[194:195]
	v_pk_fma_f32 v[194:195], v[228:229], v[158:159], v[194:195]
	v_add_f32_e32 v233, v194, v195
	ds_write2st64_b32 v100, v232, v233 offset1:8
	v_pk_fma_f32 v[196:197], v[66:67], v[130:131], v[230:231]
	v_pk_fma_f32 v[196:197], v[68:69], v[132:133], v[196:197]
	v_pk_fma_f32 v[196:197], v[70:71], v[134:135], v[196:197]
	v_pk_fma_f32 v[196:197], v[72:73], v[136:137], v[196:197]
	v_pk_fma_f32 v[196:197], v[74:75], v[138:139], v[196:197]
	v_pk_fma_f32 v[196:197], v[76:77], v[140:141], v[196:197]
	v_pk_fma_f32 v[196:197], v[78:79], v[142:143], v[196:197]
	v_pk_fma_f32 v[196:197], v[80:81], v[144:145], v[196:197]
	v_pk_fma_f32 v[196:197], v[82:83], v[146:147], v[196:197]
	v_pk_fma_f32 v[196:197], v[84:85], v[148:149], v[196:197]
	v_pk_fma_f32 v[196:197], v[86:87], v[150:151], v[196:197]
	v_pk_fma_f32 v[196:197], v[88:89], v[152:153], v[196:197]
	v_pk_fma_f32 v[196:197], v[90:91], v[154:155], v[196:197]
	v_pk_fma_f32 v[196:197], v[92:93], v[156:157], v[196:197]
	v_pk_fma_f32 v[196:197], v[94:95], v[158:159], v[196:197]
	v_fmac_f32_e32 v196, v96, v160
	v_add_f32_e32 v234, v197, v196
	v_fma_f32 v199, v66, v131, v97
	v_mov_b32_e32 v198, 0
	v_pk_fma_f32 v[198:199], v[200:201], v[132:133], v[198:199]
	v_pk_fma_f32 v[198:199], v[202:203], v[134:135], v[198:199]
	v_pk_fma_f32 v[198:199], v[204:205], v[136:137], v[198:199]
	v_pk_fma_f32 v[198:199], v[206:207], v[138:139], v[198:199]
	v_pk_fma_f32 v[198:199], v[208:209], v[140:141], v[198:199]
	v_pk_fma_f32 v[198:199], v[210:211], v[142:143], v[198:199]
	v_pk_fma_f32 v[198:199], v[212:213], v[144:145], v[198:199]
	v_pk_fma_f32 v[198:199], v[214:215], v[146:147], v[198:199]
	v_pk_fma_f32 v[198:199], v[216:217], v[148:149], v[198:199]
	v_pk_fma_f32 v[198:199], v[218:219], v[150:151], v[198:199]
	v_pk_fma_f32 v[198:199], v[220:221], v[152:153], v[198:199]
	v_pk_fma_f32 v[198:199], v[222:223], v[154:155], v[198:199]
	v_pk_fma_f32 v[198:199], v[224:225], v[156:157], v[198:199]
	v_pk_fma_f32 v[198:199], v[226:227], v[158:159], v[198:199]
	v_pk_fma_f32 v[198:199], v[228:229], v[160:161], v[198:199]
	v_add_f32_e32 v235, v198, v199
	ds_write2st64_b32 v100, v234, v235 offset0:16 offset1:24
	v_pk_fma_f32 v[192:193], v[66:67], v[132:133], v[230:231]
	v_pk_fma_f32 v[192:193], v[68:69], v[134:135], v[192:193]
	v_pk_fma_f32 v[192:193], v[70:71], v[136:137], v[192:193]
	v_pk_fma_f32 v[192:193], v[72:73], v[138:139], v[192:193]
	v_pk_fma_f32 v[192:193], v[74:75], v[140:141], v[192:193]
	v_pk_fma_f32 v[192:193], v[76:77], v[142:143], v[192:193]
	v_pk_fma_f32 v[192:193], v[78:79], v[144:145], v[192:193]
	v_pk_fma_f32 v[192:193], v[80:81], v[146:147], v[192:193]
	v_pk_fma_f32 v[192:193], v[82:83], v[148:149], v[192:193]
	v_pk_fma_f32 v[192:193], v[84:85], v[150:151], v[192:193]
	v_pk_fma_f32 v[192:193], v[86:87], v[152:153], v[192:193]
	v_pk_fma_f32 v[192:193], v[88:89], v[154:155], v[192:193]
	v_pk_fma_f32 v[192:193], v[90:91], v[156:157], v[192:193]
	v_pk_fma_f32 v[192:193], v[92:93], v[158:159], v[192:193]
	v_pk_fma_f32 v[192:193], v[94:95], v[160:161], v[192:193]
	v_fmac_f32_e32 v192, v96, v162
	v_add_f32_e32 v232, v193, v192
	v_fma_f32 v195, v66, v133, v97
	v_mov_b32_e32 v194, 0
	v_pk_fma_f32 v[194:195], v[200:201], v[134:135], v[194:195]
	v_pk_fma_f32 v[194:195], v[202:203], v[136:137], v[194:195]
	v_pk_fma_f32 v[194:195], v[204:205], v[138:139], v[194:195]
	v_pk_fma_f32 v[194:195], v[206:207], v[140:141], v[194:195]
	v_pk_fma_f32 v[194:195], v[208:209], v[142:143], v[194:195]
	v_pk_fma_f32 v[194:195], v[210:211], v[144:145], v[194:195]
	v_pk_fma_f32 v[194:195], v[212:213], v[146:147], v[194:195]
	v_pk_fma_f32 v[194:195], v[214:215], v[148:149], v[194:195]
	v_pk_fma_f32 v[194:195], v[216:217], v[150:151], v[194:195]
	v_pk_fma_f32 v[194:195], v[218:219], v[152:153], v[194:195]
	v_pk_fma_f32 v[194:195], v[220:221], v[154:155], v[194:195]
	v_pk_fma_f32 v[194:195], v[222:223], v[156:157], v[194:195]
	v_pk_fma_f32 v[194:195], v[224:225], v[158:159], v[194:195]
	v_pk_fma_f32 v[194:195], v[226:227], v[160:161], v[194:195]
	v_pk_fma_f32 v[194:195], v[228:229], v[162:163], v[194:195]
	v_add_f32_e32 v233, v194, v195
	ds_write2st64_b32 v100, v232, v233 offset0:32 offset1:40
	v_pk_fma_f32 v[196:197], v[66:67], v[134:135], v[230:231]
	v_pk_fma_f32 v[196:197], v[68:69], v[136:137], v[196:197]
	v_pk_fma_f32 v[196:197], v[70:71], v[138:139], v[196:197]
	v_pk_fma_f32 v[196:197], v[72:73], v[140:141], v[196:197]
	v_pk_fma_f32 v[196:197], v[74:75], v[142:143], v[196:197]
	v_pk_fma_f32 v[196:197], v[76:77], v[144:145], v[196:197]
	v_pk_fma_f32 v[196:197], v[78:79], v[146:147], v[196:197]
	v_pk_fma_f32 v[196:197], v[80:81], v[148:149], v[196:197]
	v_pk_fma_f32 v[196:197], v[82:83], v[150:151], v[196:197]
	v_pk_fma_f32 v[196:197], v[84:85], v[152:153], v[196:197]
	v_pk_fma_f32 v[196:197], v[86:87], v[154:155], v[196:197]
	v_pk_fma_f32 v[196:197], v[88:89], v[156:157], v[196:197]
	v_pk_fma_f32 v[196:197], v[90:91], v[158:159], v[196:197]
	v_pk_fma_f32 v[196:197], v[92:93], v[160:161], v[196:197]
	v_pk_fma_f32 v[196:197], v[94:95], v[162:163], v[196:197]
	v_fmac_f32_e32 v196, v96, v164
	v_add_f32_e32 v234, v197, v196
	v_fma_f32 v199, v66, v135, v97
	v_mov_b32_e32 v198, 0
	v_pk_fma_f32 v[198:199], v[200:201], v[136:137], v[198:199]
	v_pk_fma_f32 v[198:199], v[202:203], v[138:139], v[198:199]
	v_pk_fma_f32 v[198:199], v[204:205], v[140:141], v[198:199]
	v_pk_fma_f32 v[198:199], v[206:207], v[142:143], v[198:199]
	v_pk_fma_f32 v[198:199], v[208:209], v[144:145], v[198:199]
	v_pk_fma_f32 v[198:199], v[210:211], v[146:147], v[198:199]
	v_pk_fma_f32 v[198:199], v[212:213], v[148:149], v[198:199]
	v_pk_fma_f32 v[198:199], v[214:215], v[150:151], v[198:199]
	v_pk_fma_f32 v[198:199], v[216:217], v[152:153], v[198:199]
	v_pk_fma_f32 v[198:199], v[218:219], v[154:155], v[198:199]
	v_pk_fma_f32 v[198:199], v[220:221], v[156:157], v[198:199]
	v_pk_fma_f32 v[198:199], v[222:223], v[158:159], v[198:199]
	v_pk_fma_f32 v[198:199], v[224:225], v[160:161], v[198:199]
	v_pk_fma_f32 v[198:199], v[226:227], v[162:163], v[198:199]
	v_pk_fma_f32 v[198:199], v[228:229], v[164:165], v[198:199]
	v_add_f32_e32 v235, v198, v199
	ds_write2st64_b32 v100, v234, v235 offset0:48 offset1:56
	v_pk_fma_f32 v[192:193], v[66:67], v[136:137], v[230:231]
	v_pk_fma_f32 v[192:193], v[68:69], v[138:139], v[192:193]
	v_pk_fma_f32 v[192:193], v[70:71], v[140:141], v[192:193]
	v_pk_fma_f32 v[192:193], v[72:73], v[142:143], v[192:193]
	v_pk_fma_f32 v[192:193], v[74:75], v[144:145], v[192:193]
	v_pk_fma_f32 v[192:193], v[76:77], v[146:147], v[192:193]
	v_pk_fma_f32 v[192:193], v[78:79], v[148:149], v[192:193]
	v_pk_fma_f32 v[192:193], v[80:81], v[150:151], v[192:193]
	v_pk_fma_f32 v[192:193], v[82:83], v[152:153], v[192:193]
	v_pk_fma_f32 v[192:193], v[84:85], v[154:155], v[192:193]
	v_pk_fma_f32 v[192:193], v[86:87], v[156:157], v[192:193]
	v_pk_fma_f32 v[192:193], v[88:89], v[158:159], v[192:193]
	v_pk_fma_f32 v[192:193], v[90:91], v[160:161], v[192:193]
	v_pk_fma_f32 v[192:193], v[92:93], v[162:163], v[192:193]
	v_pk_fma_f32 v[192:193], v[94:95], v[164:165], v[192:193]
	v_fmac_f32_e32 v192, v96, v166
	v_add_f32_e32 v232, v193, v192
	v_fma_f32 v195, v66, v137, v97
	v_mov_b32_e32 v194, 0
	v_pk_fma_f32 v[194:195], v[200:201], v[138:139], v[194:195]
	v_pk_fma_f32 v[194:195], v[202:203], v[140:141], v[194:195]
	v_pk_fma_f32 v[194:195], v[204:205], v[142:143], v[194:195]
	v_pk_fma_f32 v[194:195], v[206:207], v[144:145], v[194:195]
	v_pk_fma_f32 v[194:195], v[208:209], v[146:147], v[194:195]
	v_pk_fma_f32 v[194:195], v[210:211], v[148:149], v[194:195]
	v_pk_fma_f32 v[194:195], v[212:213], v[150:151], v[194:195]
	v_pk_fma_f32 v[194:195], v[214:215], v[152:153], v[194:195]
	v_pk_fma_f32 v[194:195], v[216:217], v[154:155], v[194:195]
	v_pk_fma_f32 v[194:195], v[218:219], v[156:157], v[194:195]
	v_pk_fma_f32 v[194:195], v[220:221], v[158:159], v[194:195]
	v_pk_fma_f32 v[194:195], v[222:223], v[160:161], v[194:195]
	v_pk_fma_f32 v[194:195], v[224:225], v[162:163], v[194:195]
	v_pk_fma_f32 v[194:195], v[226:227], v[164:165], v[194:195]
	v_pk_fma_f32 v[194:195], v[228:229], v[166:167], v[194:195]
	v_add_f32_e32 v233, v194, v195
	ds_write2st64_b32 v100, v232, v233 offset0:64 offset1:72
	v_pk_fma_f32 v[196:197], v[66:67], v[138:139], v[230:231]
	v_pk_fma_f32 v[196:197], v[68:69], v[140:141], v[196:197]
	v_pk_fma_f32 v[196:197], v[70:71], v[142:143], v[196:197]
	v_pk_fma_f32 v[196:197], v[72:73], v[144:145], v[196:197]
	v_pk_fma_f32 v[196:197], v[74:75], v[146:147], v[196:197]
	v_pk_fma_f32 v[196:197], v[76:77], v[148:149], v[196:197]
	v_pk_fma_f32 v[196:197], v[78:79], v[150:151], v[196:197]
	v_pk_fma_f32 v[196:197], v[80:81], v[152:153], v[196:197]
	v_pk_fma_f32 v[196:197], v[82:83], v[154:155], v[196:197]
	v_pk_fma_f32 v[196:197], v[84:85], v[156:157], v[196:197]
	v_pk_fma_f32 v[196:197], v[86:87], v[158:159], v[196:197]
	v_pk_fma_f32 v[196:197], v[88:89], v[160:161], v[196:197]
	v_pk_fma_f32 v[196:197], v[90:91], v[162:163], v[196:197]
	v_pk_fma_f32 v[196:197], v[92:93], v[164:165], v[196:197]
	v_pk_fma_f32 v[196:197], v[94:95], v[166:167], v[196:197]
	v_fmac_f32_e32 v196, v96, v168
	v_add_f32_e32 v234, v197, v196
	v_fma_f32 v199, v66, v139, v97
	v_mov_b32_e32 v198, 0
	v_pk_fma_f32 v[198:199], v[200:201], v[140:141], v[198:199]
	v_pk_fma_f32 v[198:199], v[202:203], v[142:143], v[198:199]
	v_pk_fma_f32 v[198:199], v[204:205], v[144:145], v[198:199]
	v_pk_fma_f32 v[198:199], v[206:207], v[146:147], v[198:199]
	v_pk_fma_f32 v[198:199], v[208:209], v[148:149], v[198:199]
	v_pk_fma_f32 v[198:199], v[210:211], v[150:151], v[198:199]
	v_pk_fma_f32 v[198:199], v[212:213], v[152:153], v[198:199]
	v_pk_fma_f32 v[198:199], v[214:215], v[154:155], v[198:199]
	v_pk_fma_f32 v[198:199], v[216:217], v[156:157], v[198:199]
	v_pk_fma_f32 v[198:199], v[218:219], v[158:159], v[198:199]
	v_pk_fma_f32 v[198:199], v[220:221], v[160:161], v[198:199]
	v_pk_fma_f32 v[198:199], v[222:223], v[162:163], v[198:199]
	v_pk_fma_f32 v[198:199], v[224:225], v[164:165], v[198:199]
	v_pk_fma_f32 v[198:199], v[226:227], v[166:167], v[198:199]
	v_pk_fma_f32 v[198:199], v[228:229], v[168:169], v[198:199]
	v_add_f32_e32 v235, v198, v199
	ds_write2st64_b32 v100, v234, v235 offset0:80 offset1:88
	v_pk_fma_f32 v[192:193], v[66:67], v[140:141], v[230:231]
	v_pk_fma_f32 v[192:193], v[68:69], v[142:143], v[192:193]
	v_pk_fma_f32 v[192:193], v[70:71], v[144:145], v[192:193]
	v_pk_fma_f32 v[192:193], v[72:73], v[146:147], v[192:193]
	v_pk_fma_f32 v[192:193], v[74:75], v[148:149], v[192:193]
	v_pk_fma_f32 v[192:193], v[76:77], v[150:151], v[192:193]
	v_pk_fma_f32 v[192:193], v[78:79], v[152:153], v[192:193]
	v_pk_fma_f32 v[192:193], v[80:81], v[154:155], v[192:193]
	v_pk_fma_f32 v[192:193], v[82:83], v[156:157], v[192:193]
	v_pk_fma_f32 v[192:193], v[84:85], v[158:159], v[192:193]
	v_pk_fma_f32 v[192:193], v[86:87], v[160:161], v[192:193]
	v_pk_fma_f32 v[192:193], v[88:89], v[162:163], v[192:193]
	v_pk_fma_f32 v[192:193], v[90:91], v[164:165], v[192:193]
	v_pk_fma_f32 v[192:193], v[92:93], v[166:167], v[192:193]
	v_pk_fma_f32 v[192:193], v[94:95], v[168:169], v[192:193]
	v_fmac_f32_e32 v192, v96, v170
	v_add_f32_e32 v232, v193, v192
	v_fma_f32 v195, v66, v141, v97
	v_mov_b32_e32 v194, 0
	v_pk_fma_f32 v[194:195], v[200:201], v[142:143], v[194:195]
	v_pk_fma_f32 v[194:195], v[202:203], v[144:145], v[194:195]
	v_pk_fma_f32 v[194:195], v[204:205], v[146:147], v[194:195]
	v_pk_fma_f32 v[194:195], v[206:207], v[148:149], v[194:195]
	v_pk_fma_f32 v[194:195], v[208:209], v[150:151], v[194:195]
	v_pk_fma_f32 v[194:195], v[210:211], v[152:153], v[194:195]
	v_pk_fma_f32 v[194:195], v[212:213], v[154:155], v[194:195]
	v_pk_fma_f32 v[194:195], v[214:215], v[156:157], v[194:195]
	v_pk_fma_f32 v[194:195], v[216:217], v[158:159], v[194:195]
	v_pk_fma_f32 v[194:195], v[218:219], v[160:161], v[194:195]
	v_pk_fma_f32 v[194:195], v[220:221], v[162:163], v[194:195]
	v_pk_fma_f32 v[194:195], v[222:223], v[164:165], v[194:195]
	v_pk_fma_f32 v[194:195], v[224:225], v[166:167], v[194:195]
	v_pk_fma_f32 v[194:195], v[226:227], v[168:169], v[194:195]
	v_pk_fma_f32 v[194:195], v[228:229], v[170:171], v[194:195]
	v_add_f32_e32 v233, v194, v195
	ds_write2st64_b32 v100, v232, v233 offset0:96 offset1:104
	v_pk_fma_f32 v[196:197], v[66:67], v[142:143], v[230:231]
	v_pk_fma_f32 v[196:197], v[68:69], v[144:145], v[196:197]
	v_pk_fma_f32 v[196:197], v[70:71], v[146:147], v[196:197]
	v_pk_fma_f32 v[196:197], v[72:73], v[148:149], v[196:197]
	v_pk_fma_f32 v[196:197], v[74:75], v[150:151], v[196:197]
	v_pk_fma_f32 v[196:197], v[76:77], v[152:153], v[196:197]
	v_pk_fma_f32 v[196:197], v[78:79], v[154:155], v[196:197]
	v_pk_fma_f32 v[196:197], v[80:81], v[156:157], v[196:197]
	v_pk_fma_f32 v[196:197], v[82:83], v[158:159], v[196:197]
	v_pk_fma_f32 v[196:197], v[84:85], v[160:161], v[196:197]
	v_pk_fma_f32 v[196:197], v[86:87], v[162:163], v[196:197]
	v_pk_fma_f32 v[196:197], v[88:89], v[164:165], v[196:197]
	v_pk_fma_f32 v[196:197], v[90:91], v[166:167], v[196:197]
	v_pk_fma_f32 v[196:197], v[92:93], v[168:169], v[196:197]
	v_pk_fma_f32 v[196:197], v[94:95], v[170:171], v[196:197]
	v_fmac_f32_e32 v196, v96, v174
	v_add_f32_e32 v234, v197, v196
	v_fma_f32 v199, v66, v143, v97
	v_mov_b32_e32 v198, 0
	v_pk_fma_f32 v[198:199], v[200:201], v[144:145], v[198:199]
	v_pk_fma_f32 v[198:199], v[202:203], v[146:147], v[198:199]
	v_pk_fma_f32 v[198:199], v[204:205], v[148:149], v[198:199]
	v_pk_fma_f32 v[198:199], v[206:207], v[150:151], v[198:199]
	v_pk_fma_f32 v[198:199], v[208:209], v[152:153], v[198:199]
	v_pk_fma_f32 v[198:199], v[210:211], v[154:155], v[198:199]
	v_pk_fma_f32 v[198:199], v[212:213], v[156:157], v[198:199]
	v_pk_fma_f32 v[198:199], v[214:215], v[158:159], v[198:199]
	v_pk_fma_f32 v[198:199], v[216:217], v[160:161], v[198:199]
	v_pk_fma_f32 v[198:199], v[218:219], v[162:163], v[198:199]
	v_pk_fma_f32 v[198:199], v[220:221], v[164:165], v[198:199]
	v_pk_fma_f32 v[198:199], v[222:223], v[166:167], v[198:199]
	v_pk_fma_f32 v[198:199], v[224:225], v[168:169], v[198:199]
	v_pk_fma_f32 v[198:199], v[226:227], v[170:171], v[198:199]
	v_pk_fma_f32 v[198:199], v[228:229], v[174:175], v[198:199]
	v_add_f32_e32 v235, v198, v199
	ds_write2st64_b32 v100, v234, v235 offset0:112 offset1:120
	v_pk_fma_f32 v[192:193], v[66:67], v[144:145], v[230:231]
	v_pk_fma_f32 v[192:193], v[68:69], v[146:147], v[192:193]
	v_pk_fma_f32 v[192:193], v[70:71], v[148:149], v[192:193]
	v_pk_fma_f32 v[192:193], v[72:73], v[150:151], v[192:193]
	v_pk_fma_f32 v[192:193], v[74:75], v[152:153], v[192:193]
	v_pk_fma_f32 v[192:193], v[76:77], v[154:155], v[192:193]
	v_pk_fma_f32 v[192:193], v[78:79], v[156:157], v[192:193]
	v_pk_fma_f32 v[192:193], v[80:81], v[158:159], v[192:193]
	v_pk_fma_f32 v[192:193], v[82:83], v[160:161], v[192:193]
	v_pk_fma_f32 v[192:193], v[84:85], v[162:163], v[192:193]
	v_pk_fma_f32 v[192:193], v[86:87], v[164:165], v[192:193]
	v_pk_fma_f32 v[192:193], v[88:89], v[166:167], v[192:193]
	v_pk_fma_f32 v[192:193], v[90:91], v[168:169], v[192:193]
	v_pk_fma_f32 v[192:193], v[92:93], v[170:171], v[192:193]
	v_pk_fma_f32 v[192:193], v[94:95], v[174:175], v[192:193]
	v_fmac_f32_e32 v192, v96, v176
	v_add_f32_e32 v232, v193, v192
	v_fma_f32 v195, v66, v145, v97
	v_mov_b32_e32 v194, 0
	v_pk_fma_f32 v[194:195], v[200:201], v[146:147], v[194:195]
	v_pk_fma_f32 v[194:195], v[202:203], v[148:149], v[194:195]
	v_pk_fma_f32 v[194:195], v[204:205], v[150:151], v[194:195]
	v_pk_fma_f32 v[194:195], v[206:207], v[152:153], v[194:195]
	v_pk_fma_f32 v[194:195], v[208:209], v[154:155], v[194:195]
	v_pk_fma_f32 v[194:195], v[210:211], v[156:157], v[194:195]
	v_pk_fma_f32 v[194:195], v[212:213], v[158:159], v[194:195]
	v_pk_fma_f32 v[194:195], v[214:215], v[160:161], v[194:195]
	v_pk_fma_f32 v[194:195], v[216:217], v[162:163], v[194:195]
	v_pk_fma_f32 v[194:195], v[218:219], v[164:165], v[194:195]
	v_pk_fma_f32 v[194:195], v[220:221], v[166:167], v[194:195]
	v_pk_fma_f32 v[194:195], v[222:223], v[168:169], v[194:195]
	v_pk_fma_f32 v[194:195], v[224:225], v[170:171], v[194:195]
	v_pk_fma_f32 v[194:195], v[226:227], v[174:175], v[194:195]
	v_pk_fma_f32 v[194:195], v[228:229], v[176:177], v[194:195]
	v_add_f32_e32 v233, v194, v195
	ds_write2st64_b32 v100, v232, v233 offset0:128 offset1:136
	v_pk_fma_f32 v[196:197], v[66:67], v[146:147], v[230:231]
	v_pk_fma_f32 v[196:197], v[68:69], v[148:149], v[196:197]
	v_pk_fma_f32 v[196:197], v[70:71], v[150:151], v[196:197]
	v_pk_fma_f32 v[196:197], v[72:73], v[152:153], v[196:197]
	v_pk_fma_f32 v[196:197], v[74:75], v[154:155], v[196:197]
	v_pk_fma_f32 v[196:197], v[76:77], v[156:157], v[196:197]
	v_pk_fma_f32 v[196:197], v[78:79], v[158:159], v[196:197]
	v_pk_fma_f32 v[196:197], v[80:81], v[160:161], v[196:197]
	v_pk_fma_f32 v[196:197], v[82:83], v[162:163], v[196:197]
	v_pk_fma_f32 v[196:197], v[84:85], v[164:165], v[196:197]
	v_pk_fma_f32 v[196:197], v[86:87], v[166:167], v[196:197]
	v_pk_fma_f32 v[196:197], v[88:89], v[168:169], v[196:197]
	v_pk_fma_f32 v[196:197], v[90:91], v[170:171], v[196:197]
	v_pk_fma_f32 v[196:197], v[92:93], v[174:175], v[196:197]
	v_pk_fma_f32 v[196:197], v[94:95], v[176:177], v[196:197]
	v_fmac_f32_e32 v196, v96, v178
	v_add_f32_e32 v234, v197, v196
	v_fma_f32 v199, v66, v147, v97
	v_mov_b32_e32 v198, 0
	v_pk_fma_f32 v[198:199], v[200:201], v[148:149], v[198:199]
	v_pk_fma_f32 v[198:199], v[202:203], v[150:151], v[198:199]
	v_pk_fma_f32 v[198:199], v[204:205], v[152:153], v[198:199]
	v_pk_fma_f32 v[198:199], v[206:207], v[154:155], v[198:199]
	v_pk_fma_f32 v[198:199], v[208:209], v[156:157], v[198:199]
	v_pk_fma_f32 v[198:199], v[210:211], v[158:159], v[198:199]
	v_pk_fma_f32 v[198:199], v[212:213], v[160:161], v[198:199]
	v_pk_fma_f32 v[198:199], v[214:215], v[162:163], v[198:199]
	v_pk_fma_f32 v[198:199], v[216:217], v[164:165], v[198:199]
	v_pk_fma_f32 v[198:199], v[218:219], v[166:167], v[198:199]
	v_pk_fma_f32 v[198:199], v[220:221], v[168:169], v[198:199]
	v_pk_fma_f32 v[198:199], v[222:223], v[170:171], v[198:199]
	v_pk_fma_f32 v[198:199], v[224:225], v[174:175], v[198:199]
	v_pk_fma_f32 v[198:199], v[226:227], v[176:177], v[198:199]
	v_pk_fma_f32 v[198:199], v[228:229], v[178:179], v[198:199]
	v_add_f32_e32 v235, v198, v199
	ds_write2st64_b32 v100, v234, v235 offset0:144 offset1:152
	v_pk_fma_f32 v[192:193], v[66:67], v[148:149], v[230:231]
	v_pk_fma_f32 v[192:193], v[68:69], v[150:151], v[192:193]
	v_pk_fma_f32 v[192:193], v[70:71], v[152:153], v[192:193]
	v_pk_fma_f32 v[192:193], v[72:73], v[154:155], v[192:193]
	v_pk_fma_f32 v[192:193], v[74:75], v[156:157], v[192:193]
	v_pk_fma_f32 v[192:193], v[76:77], v[158:159], v[192:193]
	v_pk_fma_f32 v[192:193], v[78:79], v[160:161], v[192:193]
	v_pk_fma_f32 v[192:193], v[80:81], v[162:163], v[192:193]
	v_pk_fma_f32 v[192:193], v[82:83], v[164:165], v[192:193]
	v_pk_fma_f32 v[192:193], v[84:85], v[166:167], v[192:193]
	v_pk_fma_f32 v[192:193], v[86:87], v[168:169], v[192:193]
	v_pk_fma_f32 v[192:193], v[88:89], v[170:171], v[192:193]
	v_pk_fma_f32 v[192:193], v[90:91], v[174:175], v[192:193]
	v_pk_fma_f32 v[192:193], v[92:93], v[176:177], v[192:193]
	v_pk_fma_f32 v[192:193], v[94:95], v[178:179], v[192:193]
	v_fmac_f32_e32 v192, v96, v180
	v_add_f32_e32 v232, v193, v192
	v_fma_f32 v195, v66, v149, v97
	v_mov_b32_e32 v194, 0
	v_pk_fma_f32 v[194:195], v[200:201], v[150:151], v[194:195]
	v_pk_fma_f32 v[194:195], v[202:203], v[152:153], v[194:195]
	v_pk_fma_f32 v[194:195], v[204:205], v[154:155], v[194:195]
	v_pk_fma_f32 v[194:195], v[206:207], v[156:157], v[194:195]
	v_pk_fma_f32 v[194:195], v[208:209], v[158:159], v[194:195]
	v_pk_fma_f32 v[194:195], v[210:211], v[160:161], v[194:195]
	v_pk_fma_f32 v[194:195], v[212:213], v[162:163], v[194:195]
	v_pk_fma_f32 v[194:195], v[214:215], v[164:165], v[194:195]
	v_pk_fma_f32 v[194:195], v[216:217], v[166:167], v[194:195]
	v_pk_fma_f32 v[194:195], v[218:219], v[168:169], v[194:195]
	v_pk_fma_f32 v[194:195], v[220:221], v[170:171], v[194:195]
	v_pk_fma_f32 v[194:195], v[222:223], v[174:175], v[194:195]
	v_pk_fma_f32 v[194:195], v[224:225], v[176:177], v[194:195]
	v_pk_fma_f32 v[194:195], v[226:227], v[178:179], v[194:195]
	v_pk_fma_f32 v[194:195], v[228:229], v[180:181], v[194:195]
	v_add_f32_e32 v233, v194, v195
	ds_write2st64_b32 v100, v232, v233 offset0:160 offset1:168
	v_pk_fma_f32 v[196:197], v[66:67], v[150:151], v[230:231]
	v_pk_fma_f32 v[196:197], v[68:69], v[152:153], v[196:197]
	v_pk_fma_f32 v[196:197], v[70:71], v[154:155], v[196:197]
	v_pk_fma_f32 v[196:197], v[72:73], v[156:157], v[196:197]
	v_pk_fma_f32 v[196:197], v[74:75], v[158:159], v[196:197]
	v_pk_fma_f32 v[196:197], v[76:77], v[160:161], v[196:197]
	v_pk_fma_f32 v[196:197], v[78:79], v[162:163], v[196:197]
	v_pk_fma_f32 v[196:197], v[80:81], v[164:165], v[196:197]
	v_pk_fma_f32 v[196:197], v[82:83], v[166:167], v[196:197]
	v_pk_fma_f32 v[196:197], v[84:85], v[168:169], v[196:197]
	v_pk_fma_f32 v[196:197], v[86:87], v[170:171], v[196:197]
	v_pk_fma_f32 v[196:197], v[88:89], v[174:175], v[196:197]
	v_pk_fma_f32 v[196:197], v[90:91], v[176:177], v[196:197]
	v_pk_fma_f32 v[196:197], v[92:93], v[178:179], v[196:197]
	v_pk_fma_f32 v[196:197], v[94:95], v[180:181], v[196:197]
	v_fmac_f32_e32 v196, v96, v182
	v_add_f32_e32 v234, v197, v196
	v_fma_f32 v199, v66, v151, v97
	v_mov_b32_e32 v198, 0
	v_pk_fma_f32 v[198:199], v[200:201], v[152:153], v[198:199]
	v_pk_fma_f32 v[198:199], v[202:203], v[154:155], v[198:199]
	v_pk_fma_f32 v[198:199], v[204:205], v[156:157], v[198:199]
	v_pk_fma_f32 v[198:199], v[206:207], v[158:159], v[198:199]
	v_pk_fma_f32 v[198:199], v[208:209], v[160:161], v[198:199]
	v_pk_fma_f32 v[198:199], v[210:211], v[162:163], v[198:199]
	v_pk_fma_f32 v[198:199], v[212:213], v[164:165], v[198:199]
	v_pk_fma_f32 v[198:199], v[214:215], v[166:167], v[198:199]
	v_pk_fma_f32 v[198:199], v[216:217], v[168:169], v[198:199]
	v_pk_fma_f32 v[198:199], v[218:219], v[170:171], v[198:199]
	v_pk_fma_f32 v[198:199], v[220:221], v[174:175], v[198:199]
	v_pk_fma_f32 v[198:199], v[222:223], v[176:177], v[198:199]
	v_pk_fma_f32 v[198:199], v[224:225], v[178:179], v[198:199]
	v_pk_fma_f32 v[198:199], v[226:227], v[180:181], v[198:199]
	v_pk_fma_f32 v[198:199], v[228:229], v[182:183], v[198:199]
	v_add_f32_e32 v235, v198, v199
	ds_write2st64_b32 v100, v234, v235 offset0:176 offset1:184
	v_pk_fma_f32 v[192:193], v[66:67], v[152:153], v[230:231]
	v_pk_fma_f32 v[192:193], v[68:69], v[154:155], v[192:193]
	v_pk_fma_f32 v[192:193], v[70:71], v[156:157], v[192:193]
	v_pk_fma_f32 v[192:193], v[72:73], v[158:159], v[192:193]
	v_pk_fma_f32 v[192:193], v[74:75], v[160:161], v[192:193]
	v_pk_fma_f32 v[192:193], v[76:77], v[162:163], v[192:193]
	v_pk_fma_f32 v[192:193], v[78:79], v[164:165], v[192:193]
	v_pk_fma_f32 v[192:193], v[80:81], v[166:167], v[192:193]
	v_pk_fma_f32 v[192:193], v[82:83], v[168:169], v[192:193]
	v_pk_fma_f32 v[192:193], v[84:85], v[170:171], v[192:193]
	v_pk_fma_f32 v[192:193], v[86:87], v[174:175], v[192:193]
	v_pk_fma_f32 v[192:193], v[88:89], v[176:177], v[192:193]
	v_pk_fma_f32 v[192:193], v[90:91], v[178:179], v[192:193]
	v_pk_fma_f32 v[192:193], v[92:93], v[180:181], v[192:193]
	v_pk_fma_f32 v[192:193], v[94:95], v[182:183], v[192:193]
	v_fmac_f32_e32 v192, v96, v184
	v_add_f32_e32 v232, v193, v192
	v_fma_f32 v195, v66, v153, v97
	v_mov_b32_e32 v194, 0
	v_pk_fma_f32 v[194:195], v[200:201], v[154:155], v[194:195]
	v_pk_fma_f32 v[194:195], v[202:203], v[156:157], v[194:195]
	v_pk_fma_f32 v[194:195], v[204:205], v[158:159], v[194:195]
	v_pk_fma_f32 v[194:195], v[206:207], v[160:161], v[194:195]
	v_pk_fma_f32 v[194:195], v[208:209], v[162:163], v[194:195]
	v_pk_fma_f32 v[194:195], v[210:211], v[164:165], v[194:195]
	v_pk_fma_f32 v[194:195], v[212:213], v[166:167], v[194:195]
	v_pk_fma_f32 v[194:195], v[214:215], v[168:169], v[194:195]
	v_pk_fma_f32 v[194:195], v[216:217], v[170:171], v[194:195]
	v_pk_fma_f32 v[194:195], v[218:219], v[174:175], v[194:195]
	v_pk_fma_f32 v[194:195], v[220:221], v[176:177], v[194:195]
	v_pk_fma_f32 v[194:195], v[222:223], v[178:179], v[194:195]
	v_pk_fma_f32 v[194:195], v[224:225], v[180:181], v[194:195]
	v_pk_fma_f32 v[194:195], v[226:227], v[182:183], v[194:195]
	v_pk_fma_f32 v[194:195], v[228:229], v[184:185], v[194:195]
	v_add_f32_e32 v233, v194, v195
	ds_write2st64_b32 v100, v232, v233 offset0:192 offset1:200
	v_pk_fma_f32 v[196:197], v[66:67], v[154:155], v[230:231]
	v_pk_fma_f32 v[196:197], v[68:69], v[156:157], v[196:197]
	v_pk_fma_f32 v[196:197], v[70:71], v[158:159], v[196:197]
	v_pk_fma_f32 v[196:197], v[72:73], v[160:161], v[196:197]
	v_pk_fma_f32 v[196:197], v[74:75], v[162:163], v[196:197]
	v_pk_fma_f32 v[196:197], v[76:77], v[164:165], v[196:197]
	v_pk_fma_f32 v[196:197], v[78:79], v[166:167], v[196:197]
	v_pk_fma_f32 v[196:197], v[80:81], v[168:169], v[196:197]
	v_pk_fma_f32 v[196:197], v[82:83], v[170:171], v[196:197]
	v_pk_fma_f32 v[196:197], v[84:85], v[174:175], v[196:197]
	v_pk_fma_f32 v[196:197], v[86:87], v[176:177], v[196:197]
	v_pk_fma_f32 v[196:197], v[88:89], v[178:179], v[196:197]
	v_pk_fma_f32 v[196:197], v[90:91], v[180:181], v[196:197]
	v_pk_fma_f32 v[196:197], v[92:93], v[182:183], v[196:197]
	v_pk_fma_f32 v[196:197], v[94:95], v[184:185], v[196:197]
	v_fmac_f32_e32 v196, v96, v186
	v_add_f32_e32 v234, v197, v196
	v_fma_f32 v199, v66, v155, v97
	v_mov_b32_e32 v198, 0
	v_pk_fma_f32 v[198:199], v[200:201], v[156:157], v[198:199]
	v_pk_fma_f32 v[198:199], v[202:203], v[158:159], v[198:199]
	v_pk_fma_f32 v[198:199], v[204:205], v[160:161], v[198:199]
	v_pk_fma_f32 v[198:199], v[206:207], v[162:163], v[198:199]
	v_pk_fma_f32 v[198:199], v[208:209], v[164:165], v[198:199]
	v_pk_fma_f32 v[198:199], v[210:211], v[166:167], v[198:199]
	v_pk_fma_f32 v[198:199], v[212:213], v[168:169], v[198:199]
	v_pk_fma_f32 v[198:199], v[214:215], v[170:171], v[198:199]
	v_pk_fma_f32 v[198:199], v[216:217], v[174:175], v[198:199]
	v_pk_fma_f32 v[198:199], v[218:219], v[176:177], v[198:199]
	v_pk_fma_f32 v[198:199], v[220:221], v[178:179], v[198:199]
	v_pk_fma_f32 v[198:199], v[222:223], v[180:181], v[198:199]
	v_pk_fma_f32 v[198:199], v[224:225], v[182:183], v[198:199]
	v_pk_fma_f32 v[198:199], v[226:227], v[184:185], v[198:199]
	v_pk_fma_f32 v[198:199], v[228:229], v[186:187], v[198:199]
	v_add_f32_e32 v235, v198, v199
	ds_write2st64_b32 v100, v234, v235 offset0:208 offset1:216
	v_pk_fma_f32 v[192:193], v[66:67], v[156:157], v[230:231]
	v_pk_fma_f32 v[192:193], v[68:69], v[158:159], v[192:193]
	v_pk_fma_f32 v[192:193], v[70:71], v[160:161], v[192:193]
	v_pk_fma_f32 v[192:193], v[72:73], v[162:163], v[192:193]
	v_pk_fma_f32 v[192:193], v[74:75], v[164:165], v[192:193]
	v_pk_fma_f32 v[192:193], v[76:77], v[166:167], v[192:193]
	v_pk_fma_f32 v[192:193], v[78:79], v[168:169], v[192:193]
	v_pk_fma_f32 v[192:193], v[80:81], v[170:171], v[192:193]
	v_pk_fma_f32 v[192:193], v[82:83], v[174:175], v[192:193]
	v_pk_fma_f32 v[192:193], v[84:85], v[176:177], v[192:193]
	v_pk_fma_f32 v[192:193], v[86:87], v[178:179], v[192:193]
	v_pk_fma_f32 v[192:193], v[88:89], v[180:181], v[192:193]
	v_pk_fma_f32 v[192:193], v[90:91], v[182:183], v[192:193]
	v_pk_fma_f32 v[192:193], v[92:93], v[184:185], v[192:193]
	v_pk_fma_f32 v[192:193], v[94:95], v[186:187], v[192:193]
	v_fmac_f32_e32 v192, v96, v188
	v_add_f32_e32 v232, v193, v192
	v_fma_f32 v195, v66, v157, v97
	v_mov_b32_e32 v194, 0
	v_pk_fma_f32 v[194:195], v[200:201], v[158:159], v[194:195]
	v_pk_fma_f32 v[194:195], v[202:203], v[160:161], v[194:195]
	v_pk_fma_f32 v[194:195], v[204:205], v[162:163], v[194:195]
	v_pk_fma_f32 v[194:195], v[206:207], v[164:165], v[194:195]
	v_pk_fma_f32 v[194:195], v[208:209], v[166:167], v[194:195]
	v_pk_fma_f32 v[194:195], v[210:211], v[168:169], v[194:195]
	v_pk_fma_f32 v[194:195], v[212:213], v[170:171], v[194:195]
	v_pk_fma_f32 v[194:195], v[214:215], v[174:175], v[194:195]
	v_pk_fma_f32 v[194:195], v[216:217], v[176:177], v[194:195]
	v_pk_fma_f32 v[194:195], v[218:219], v[178:179], v[194:195]
	v_pk_fma_f32 v[194:195], v[220:221], v[180:181], v[194:195]
	v_pk_fma_f32 v[194:195], v[222:223], v[182:183], v[194:195]
	v_pk_fma_f32 v[194:195], v[224:225], v[184:185], v[194:195]
	v_pk_fma_f32 v[194:195], v[226:227], v[186:187], v[194:195]
	v_pk_fma_f32 v[194:195], v[228:229], v[188:189], v[194:195]
	v_add_f32_e32 v233, v194, v195
	ds_write2st64_b32 v100, v232, v233 offset0:224 offset1:232
	v_pk_fma_f32 v[196:197], v[66:67], v[158:159], v[230:231]
	v_pk_fma_f32 v[196:197], v[68:69], v[160:161], v[196:197]
	v_pk_fma_f32 v[196:197], v[70:71], v[162:163], v[196:197]
	v_pk_fma_f32 v[196:197], v[72:73], v[164:165], v[196:197]
	v_pk_fma_f32 v[196:197], v[74:75], v[166:167], v[196:197]
	v_pk_fma_f32 v[196:197], v[76:77], v[168:169], v[196:197]
	v_pk_fma_f32 v[196:197], v[78:79], v[170:171], v[196:197]
	v_pk_fma_f32 v[196:197], v[80:81], v[174:175], v[196:197]
	v_pk_fma_f32 v[196:197], v[82:83], v[176:177], v[196:197]
	v_pk_fma_f32 v[196:197], v[84:85], v[178:179], v[196:197]
	v_pk_fma_f32 v[196:197], v[86:87], v[180:181], v[196:197]
	v_pk_fma_f32 v[196:197], v[88:89], v[182:183], v[196:197]
	v_pk_fma_f32 v[196:197], v[90:91], v[184:185], v[196:197]
	v_pk_fma_f32 v[196:197], v[92:93], v[186:187], v[196:197]
	v_pk_fma_f32 v[196:197], v[94:95], v[188:189], v[196:197]
	v_fmac_f32_e32 v196, v96, v190
	v_add_f32_e32 v234, v197, v196
	v_fma_f32 v199, v66, v159, v97
	v_mov_b32_e32 v198, 0
	v_pk_fma_f32 v[198:199], v[200:201], v[160:161], v[198:199]
	v_pk_fma_f32 v[198:199], v[202:203], v[162:163], v[198:199]
	v_pk_fma_f32 v[198:199], v[204:205], v[164:165], v[198:199]
	v_pk_fma_f32 v[198:199], v[206:207], v[166:167], v[198:199]
	v_pk_fma_f32 v[198:199], v[208:209], v[168:169], v[198:199]
	v_pk_fma_f32 v[198:199], v[210:211], v[170:171], v[198:199]
	v_pk_fma_f32 v[198:199], v[212:213], v[174:175], v[198:199]
	v_pk_fma_f32 v[198:199], v[214:215], v[176:177], v[198:199]
	v_pk_fma_f32 v[198:199], v[216:217], v[178:179], v[198:199]
	v_pk_fma_f32 v[198:199], v[218:219], v[180:181], v[198:199]
	v_pk_fma_f32 v[198:199], v[220:221], v[182:183], v[198:199]
	v_pk_fma_f32 v[198:199], v[222:223], v[184:185], v[198:199]
	v_pk_fma_f32 v[198:199], v[224:225], v[186:187], v[198:199]
	v_pk_fma_f32 v[198:199], v[226:227], v[188:189], v[198:199]
	v_pk_fma_f32 v[198:199], v[228:229], v[190:191], v[198:199]
	v_add_f32_e32 v235, v198, v199
	ds_write2st64_b32 v100, v234, v235 offset0:240 offset1:248
	s_waitcnt lgkmcnt(0)
	s_barrier
	ds_read_b128 v[128:131], v122
	ds_read_b128 v[132:135], v122 offset:16
	s_ashr_i32 s0, s40, 31
	s_lshr_b32 s0, s0, 26
	s_add_i32 s1, s40, s0
	s_waitcnt lgkmcnt(1)
	v_mov_b32_e32 v34, v129
	v_mov_b32_e32 v35, v130
	v_mov_b32_e32 v64, v128
	v_mov_b32_e32 v65, v131
	v_pk_add_f32 v[34:35], v[34:35], v[64:65]
	s_waitcnt lgkmcnt(0)
	v_mov_b32_e32 v64, v134
	v_mov_b32_e32 v65, v132
	v_mov_b32_e32 v136, v135
	v_mov_b32_e32 v137, v133
	v_pk_add_f32 v[64:65], v[64:65], v[136:137]
	v_add_f32_e32 v33, v34, v35
	v_add_f32_e32 v33, v33, v65
	v_add_f32_e32 v33, v64, v33
	ds_bpermute_b32 v34, v101, v33
	s_ashr_i32 s0, s1, 6
	s_and_b32 s1, s1, 0x7ffffc0
	s_sub_i32 s20, s40, s1
	s_ashr_i32 s1, s0, 31
	s_waitcnt lgkmcnt(0)
	v_add_f32_e32 v33, v33, v34
	ds_bpermute_b32 v34, v102, v33
	s_lshl_b32 s33, s20, 5
	s_lshl_b64 s[20:21], s[0:1], 11
	s_waitcnt lgkmcnt(0)
	v_add_f32_e32 v33, v33, v34
	ds_bpermute_b32 v34, v103, v33
	s_waitcnt lgkmcnt(0)
	v_add_f32_e32 v33, v33, v34
	ds_bpermute_b32 v34, v104, v33
	s_waitcnt lgkmcnt(0)
	v_add_f32_e32 v33, v33, v34
	ds_bpermute_b32 v34, v105, v33
	s_waitcnt lgkmcnt(0)
	v_add_f32_e32 v33, v33, v34
	ds_bpermute_b32 v34, v106, v33
	s_waitcnt lgkmcnt(0)
	v_add_f32_e32 v33, v33, v34
	v_fmamk_f32 v35, v33, 0xbb000000, v131
	v_fmac_f32_e32 v129, 0xbb000000, v33
	v_fmamk_f32 v34, v33, 0xbb000000, v130
	v_fmamk_f32 v128, v33, 0xbb000000, v128
	v_fmamk_f32 v65, v33, 0xbb000000, v133
	v_fmamk_f32 v64, v33, 0xbb000000, v132
	v_fmamk_f32 v135, v33, 0xbb000000, v135
	v_fmac_f32_e32 v134, 0xbb000000, v33
	v_mul_f32_e32 v33, v129, v129
	v_mul_f32_e32 v130, v35, v35
	v_fmac_f32_e32 v33, v128, v128
	v_fmac_f32_e32 v130, v34, v34
	v_add_f32_e32 v33, v33, v130
	v_pk_mul_f32 v[130:131], v[134:135], v[134:135]
	v_pk_mul_f32 v[132:133], v[64:65], v[64:65]
	v_mov_b32_e32 v136, v130
	v_mov_b32_e32 v137, v132
	v_mov_b32_e32 v132, v131
	v_pk_add_f32 v[130:131], v[136:137], v[132:133]
	s_nop 0
	v_add_f32_e32 v33, v131, v33
	v_add_f32_e32 v33, v130, v33
	ds_bpermute_b32 v130, v101, v33
	s_waitcnt lgkmcnt(0)
	v_add_f32_e32 v33, v33, v130
	ds_bpermute_b32 v130, v102, v33
	s_waitcnt lgkmcnt(0)
	v_add_f32_e32 v33, v33, v130
	ds_bpermute_b32 v130, v103, v33
	s_waitcnt lgkmcnt(0)
	v_add_f32_e32 v33, v33, v130
	ds_bpermute_b32 v130, v104, v33
	s_waitcnt lgkmcnt(0)
	v_add_f32_e32 v33, v33, v130
	ds_bpermute_b32 v130, v105, v33
	s_waitcnt lgkmcnt(0)
	v_add_f32_e32 v33, v33, v130
	ds_bpermute_b32 v130, v106, v33
	s_waitcnt lgkmcnt(0)
	v_add_f32_e32 v33, v33, v130
	v_fmamk_f32 v33, v33, 0x3b000000, v123
	v_mul_f32_e32 v130, 0x4f800000, v33
	v_cmp_gt_f32_e32 vcc, s45, v33
	s_nop 1
	v_cndmask_b32_e32 v33, v33, v130, vcc
	v_sqrt_f32_e32 v130, v33
	s_nop 0
	v_add_u32_e32 v131, -1, v130
	v_fma_f32 v132, -v131, v130, v33
	v_cmp_ge_f32_e64 s[0:1], 0, v132
	v_add_u32_e32 v132, 1, v130
	s_nop 0
	v_cndmask_b32_e64 v131, v130, v131, s[0:1]
	v_fma_f32 v130, -v132, v130, v33
	v_cmp_lt_f32_e64 s[0:1], 0, v130
	s_nop 1
	v_cndmask_b32_e64 v130, v131, v132, s[0:1]
	v_mul_f32_e32 v131, 0x37800000, v130
	v_cndmask_b32_e32 v130, v130, v131, vcc
	v_cmp_class_f32_e32 vcc, v33, v124
	s_nop 1
	v_cndmask_b32_e32 v33, v130, v33, vcc
	v_div_scale_f32 v130, s[0:1], v33, v33, 1.0
	v_rcp_f32_e32 v131, v130
	s_ashr_i32 s0, s33, 31
	s_add_u32 s40, s20, s33
	s_addc_u32 s41, s21, s0
	v_fma_f32 v132, -v130, v131, 1.0
	v_fmac_f32_e32 v131, v132, v131
	v_div_scale_f32 v132, vcc, 1.0, v33, 1.0
	v_mul_f32_e32 v133, v132, v131
	v_fma_f32 v136, -v130, v133, v132
	v_fmac_f32_e32 v133, v136, v131
	v_fma_f32 v130, -v130, v133, v132
	v_div_fmas_f32 v130, v130, v131, v133
	v_div_fixup_f32 v130, v130, v33, 1.0
	v_pk_mul_f32 v[128:129], v[128:129], v[130:131] op_sel_hi:[1,0]
	v_pk_mul_f32 v[64:65], v[64:65], v[130:131] op_sel_hi:[1,0]
	s_waitcnt vmcnt(0)
	v_pk_fma_f32 v[136:137], v[8:9], v[128:129], v[12:13]
	v_pk_mul_f32 v[128:129], v[134:135], v[130:131] op_sel_hi:[1,0]
	v_pk_fma_f32 v[64:65], v[0:1], v[64:65], v[4:5]
	v_mul_f32_e32 v33, 0xbfb8aa3b, v136
	v_pk_mul_f32 v[34:35], v[34:35], v[130:131] op_sel_hi:[1,0]
	v_exp_f32_e32 v33, v33
	v_mul_f32_e32 v130, 0xbfb8aa3b, v64
	v_pk_fma_f32 v[138:139], v[2:3], v[128:129], v[6:7]
	v_mul_f32_e32 v128, 0xbfb8aa3b, v137
	v_exp_f32_e32 v130, v130
	v_exp_f32_e32 v128, v128
	v_add_f32_e32 v33, 1.0, v33
	v_rcp_f32_e32 v140, v33
	v_add_f32_e32 v33, 1.0, v130
	v_add_f32_e32 v132, 1.0, v128
	ds_read_b128 v[128:131], v125
	v_rcp_f32_e32 v142, v33
	v_mul_f32_e32 v33, 0xbfb8aa3b, v65
	v_rcp_f32_e32 v144, v132
	ds_read_b128 v[132:135], v125 offset:16
	v_exp_f32_e32 v33, v33
	s_waitcnt lgkmcnt(1)
	v_mov_b32_e32 v148, v129
	v_mov_b32_e32 v149, v130
	v_mov_b32_e32 v150, v128
	v_mov_b32_e32 v151, v131
	v_add_f32_e32 v33, 1.0, v33
	v_pk_add_f32 v[148:149], v[148:149], v[150:151]
	s_waitcnt lgkmcnt(0)
	v_mov_b32_e32 v150, v134
	v_mov_b32_e32 v151, v132
	v_mov_b32_e32 v152, v135
	v_mov_b32_e32 v153, v133
	v_rcp_f32_e32 v146, v33
	v_pk_add_f32 v[150:151], v[150:151], v[152:153]
	v_add_f32_e32 v33, v148, v149
	v_add_f32_e32 v33, v33, v151
	v_add_f32_e32 v33, v150, v33
	ds_bpermute_b32 v141, v101, v33
	v_pk_fma_f32 v[34:35], v[10:11], v[34:35], v[14:15]
	v_mul_f32_e32 v145, 0xbfb8aa3b, v138
	v_mul_f32_e32 v143, 0xbfb8aa3b, v34
	v_exp_f32_e32 v143, v143
	s_waitcnt lgkmcnt(0)
	v_add_f32_e32 v33, v33, v141
	ds_bpermute_b32 v147, v102, v33
	v_exp_f32_e32 v145, v145
	v_add_f32_e32 v141, 1.0, v143
	v_mul_f32_e32 v148, 0xbfb8aa3b, v139
	v_exp_f32_e32 v148, v148
	s_waitcnt lgkmcnt(0)
	v_add_f32_e32 v33, v33, v147
	v_add_f32_e32 v143, 1.0, v145
	ds_bpermute_b32 v145, v103, v33
	v_mul_f32_e32 v147, 0xbfb8aa3b, v35
	v_exp_f32_e32 v147, v147
	v_rcp_f32_e32 v141, v141
	v_rcp_f32_e32 v143, v143
	s_waitcnt lgkmcnt(0)
	v_add_f32_e32 v33, v33, v145
	ds_bpermute_b32 v149, v104, v33
	v_add_f32_e32 v145, 1.0, v147
	v_add_f32_e32 v147, 1.0, v148
	v_mov_b32_e32 v148, v136
	v_rcp_f32_e32 v145, v145
	s_waitcnt lgkmcnt(0)
	v_add_f32_e32 v33, v33, v149
	ds_bpermute_b32 v150, v105, v33
	v_mov_b32_e32 v149, v34
	v_pk_mul_f32 v[140:141], v[148:149], v[140:141]
	v_mov_b32_e32 v34, v137
	v_mov_b32_e32 v136, v64
	s_waitcnt lgkmcnt(0)
	v_add_f32_e32 v33, v33, v150
	ds_bpermute_b32 v148, v106, v33
	v_mov_b32_e32 v137, v138
	v_pk_mul_f32 v[34:35], v[34:35], v[144:145]
	v_pk_mul_f32 v[136:137], v[136:137], v[142:143]
	v_rcp_f32_e32 v147, v147
	s_waitcnt lgkmcnt(0)
	v_add_f32_e32 v33, v33, v148
	v_fmamk_f32 v143, v33, 0xbb000000, v131
	v_fmac_f32_e32 v129, 0xbb000000, v33
	v_fmamk_f32 v145, v33, 0xbb000000, v133
	v_fmamk_f32 v144, v33, 0xbb000000, v132
	v_fmamk_f32 v135, v33, 0xbb000000, v135
	v_fmac_f32_e32 v134, 0xbb000000, v33
	v_fmamk_f32 v142, v33, 0xbb000000, v130
	v_fmamk_f32 v128, v33, 0xbb000000, v128
	v_mul_f32_e32 v33, v129, v129
	v_mul_f32_e32 v64, v143, v143
	v_pk_mul_f32 v[130:131], v[134:135], v[134:135]
	v_pk_mul_f32 v[132:133], v[144:145], v[144:145]
	v_fmac_f32_e32 v33, v128, v128
	v_fmac_f32_e32 v64, v142, v142
	v_mov_b32_e32 v148, v130
	v_mov_b32_e32 v149, v132
	v_mov_b32_e32 v132, v131
	v_add_f32_e32 v33, v33, v64
	v_pk_add_f32 v[130:131], v[148:149], v[132:133]
	v_mov_b32_e32 v138, v65
	v_add_f32_e32 v33, v131, v33
	v_add_f32_e32 v33, v130, v33
	ds_bpermute_b32 v130, v101, v33
	v_pk_mul_f32 v[64:65], v[138:139], v[146:147]
	v_bfe_u32 v133, v35, 16, 1
	v_bfe_u32 v131, v65, 16, 1
	v_bfe_u32 v132, v64, 16, 1
	s_waitcnt lgkmcnt(0)
	v_add_f32_e32 v33, v33, v130
	ds_bpermute_b32 v130, v102, v33
	v_add3_u32 v35, v35, v133, s52
	v_add3_u32 v64, v64, v132, s52
	v_add3_u32 v65, v65, v131, s52
	v_bfe_u32 v131, v140, 16, 1
	s_waitcnt lgkmcnt(0)
	v_add_f32_e32 v33, v33, v130
	ds_bpermute_b32 v130, v103, v33
	v_bfe_u32 v132, v141, 16, 1
	v_bfe_u32 v133, v136, 16, 1
	v_add3_u32 v133, v136, v133, s52
	v_add3_u32 v132, v141, v132, s52
	s_waitcnt lgkmcnt(0)
	v_add_f32_e32 v33, v33, v130
	ds_bpermute_b32 v130, v104, v33
	v_add3_u32 v131, v140, v131, s52
	v_lshrrev_b32_e32 v136, 16, v131
	v_lshrrev_b32_e32 v131, 16, v132
	v_lshrrev_b32_e32 v132, 16, v133
	s_waitcnt lgkmcnt(0)
	v_add_f32_e32 v33, v33, v130
	ds_bpermute_b32 v130, v105, v33
	v_and_or_b32 v132, v64, s53, v132
	v_bfe_u32 v138, v34, 16, 1
	v_add3_u32 v34, v34, v138, s52
	v_bfe_u32 v138, v137, 16, 1
	s_waitcnt lgkmcnt(0)
	v_add_f32_e32 v33, v33, v130
	ds_bpermute_b32 v130, v106, v33
	v_add3_u32 v137, v137, v138, s52
	v_lshrrev_b32_e32 v133, 16, v137
	v_and_or_b32 v133, v65, s53, v133
	v_and_or_b32 v131, v35, s53, v131
	s_waitcnt lgkmcnt(0)
	v_add_f32_e32 v33, v33, v130
	v_fmamk_f32 v33, v33, 0x3b000000, v123
	v_mul_f32_e32 v64, 0x4f800000, v33
	v_cmp_gt_f32_e32 vcc, s45, v33
	v_and_or_b32 v130, v34, s53, v136
	v_lshl_add_u64 v[34:35], s[40:41], 0, v[54:55]
	v_cndmask_b32_e32 v33, v33, v64, vcc
	v_sqrt_f32_e32 v64, v33
	v_lshlrev_b64 v[34:35], 11, v[34:35]
	v_lshl_add_u64 v[34:35], v[62:63], 0, v[34:35]
	global_store_dwordx4 v[34:35], v[130:133], off offset:1024
	v_add_u32_e32 v65, -1, v64
	v_fma_f32 v136, -v65, v64, v33
	v_cmp_ge_f32_e64 s[0:1], 0, v136
	v_add_u32_e32 v136, 1, v64
	s_add_i32 s43, s43, 32
	v_cndmask_b32_e64 v65, v64, v65, s[0:1]
	v_fma_f32 v64, -v136, v64, v33
	v_cmp_lt_f32_e64 s[0:1], 0, v64
	s_cmp_lg_u32 s42, s44
	s_nop 0
	v_cndmask_b32_e64 v64, v65, v136, s[0:1]
	v_mul_f32_e32 v65, 0x37800000, v64
	v_cndmask_b32_e32 v64, v64, v65, vcc
	v_cmp_class_f32_e32 vcc, v33, v124
	s_nop 1
	v_cndmask_b32_e32 v33, v64, v33, vcc
	v_div_scale_f32 v64, s[0:1], v33, v33, 1.0
	v_rcp_f32_e32 v65, v64
	s_nop 0
	v_fma_f32 v34, -v64, v65, 1.0
	v_fmac_f32_e32 v65, v34, v65
	v_div_scale_f32 v34, vcc, 1.0, v33, 1.0
	v_mul_f32_e32 v35, v34, v65
	v_fma_f32 v130, -v64, v35, v34
	v_fmac_f32_e32 v35, v130, v65
	v_fma_f32 v34, -v64, v35, v34
	v_div_fmas_f32 v34, v34, v65, v35
	v_div_fixup_f32 v34, v34, v33, 1.0
	v_pk_mul_f32 v[64:65], v[128:129], v[34:35] op_sel_hi:[1,0]
	v_pk_mul_f32 v[128:129], v[142:143], v[34:35] op_sel_hi:[1,0]
	v_pk_fma_f32 v[64:65], v[8:9], v[64:65], v[12:13]
	v_pk_fma_f32 v[136:137], v[10:11], v[128:129], v[14:15]
	v_pk_mul_f32 v[128:129], v[144:145], v[34:35] op_sel_hi:[1,0]
	v_mul_f32_e32 v33, 0xbfb8aa3b, v64
	v_pk_fma_f32 v[138:139], v[0:1], v[128:129], v[4:5]
	v_exp_f32_e32 v33, v33
	v_mul_f32_e32 v128, 0xbfb8aa3b, v138
	v_exp_f32_e32 v128, v128
	v_pk_mul_f32 v[34:35], v[134:135], v[34:35] op_sel_hi:[1,0]
	v_add_f32_e32 v33, 1.0, v33
	v_rcp_f32_e32 v140, v33
	v_add_f32_e32 v33, 1.0, v128
	v_mul_f32_e32 v128, 0xbfb8aa3b, v65
	v_exp_f32_e32 v128, v128
	v_rcp_f32_e32 v142, v33
	v_mul_f32_e32 v33, 0xbfb8aa3b, v139
	v_exp_f32_e32 v33, v33
	v_add_f32_e32 v132, 1.0, v128
	ds_read_b128 v[128:131], v126
	v_rcp_f32_e32 v144, v132
	ds_read_b128 v[132:135], v126 offset:16
	v_add_f32_e32 v33, 1.0, v33
	v_rcp_f32_e32 v146, v33
	s_waitcnt lgkmcnt(1)
	v_mov_b32_e32 v148, v129
	v_mov_b32_e32 v149, v130
	v_mov_b32_e32 v150, v128
	v_mov_b32_e32 v151, v131
	v_pk_add_f32 v[148:149], v[148:149], v[150:151]
	s_waitcnt lgkmcnt(0)
	v_mov_b32_e32 v150, v134
	v_mov_b32_e32 v151, v132
	v_mov_b32_e32 v152, v135
	v_mov_b32_e32 v153, v133
	v_pk_add_f32 v[150:151], v[150:151], v[152:153]
	v_add_f32_e32 v33, v148, v149
	v_add_f32_e32 v33, v33, v151
	v_add_f32_e32 v33, v150, v33
	ds_bpermute_b32 v141, v101, v33
	v_pk_fma_f32 v[34:35], v[2:3], v[34:35], v[6:7]
	v_mul_f32_e32 v143, 0xbfb8aa3b, v136
	v_mul_f32_e32 v145, 0xbfb8aa3b, v34
	v_exp_f32_e32 v143, v143
	s_waitcnt lgkmcnt(0)
	v_add_f32_e32 v33, v33, v141
	ds_bpermute_b32 v147, v102, v33
	v_exp_f32_e32 v145, v145
	v_add_f32_e32 v141, 1.0, v143
	v_mul_f32_e32 v148, 0xbfb8aa3b, v35
	v_exp_f32_e32 v148, v148
	s_waitcnt lgkmcnt(0)
	v_add_f32_e32 v33, v33, v147
	v_add_f32_e32 v143, 1.0, v145
	ds_bpermute_b32 v145, v103, v33
	v_mul_f32_e32 v147, 0xbfb8aa3b, v137
	v_exp_f32_e32 v147, v147
	v_rcp_f32_e32 v141, v141
	v_rcp_f32_e32 v143, v143
	s_waitcnt lgkmcnt(0)
	v_add_f32_e32 v33, v33, v145
	ds_bpermute_b32 v149, v104, v33
	v_add_f32_e32 v145, 1.0, v147
	v_add_f32_e32 v147, 1.0, v148
	v_mov_b32_e32 v148, v64
	v_rcp_f32_e32 v145, v145
	s_waitcnt lgkmcnt(0)
	v_add_f32_e32 v33, v33, v149
	ds_bpermute_b32 v150, v105, v33
	v_mov_b32_e32 v149, v136
	v_pk_mul_f32 v[140:141], v[148:149], v[140:141]
	v_mov_b32_e32 v136, v65
	v_pk_mul_f32 v[64:65], v[136:137], v[144:145]
	s_waitcnt lgkmcnt(0)
	v_add_f32_e32 v33, v33, v150
	ds_bpermute_b32 v148, v106, v33
	v_mov_b32_e32 v136, v138
	v_mov_b32_e32 v137, v34
	v_pk_mul_f32 v[136:137], v[136:137], v[142:143]
	v_rcp_f32_e32 v147, v147
	s_waitcnt lgkmcnt(0)
	v_add_f32_e32 v33, v33, v148
	v_fmamk_f32 v143, v33, 0xbb000000, v131
	v_fmac_f32_e32 v129, 0xbb000000, v33
	v_fmamk_f32 v145, v33, 0xbb000000, v133
	v_fmamk_f32 v144, v33, 0xbb000000, v132
	v_fmamk_f32 v135, v33, 0xbb000000, v135
	v_fmac_f32_e32 v134, 0xbb000000, v33
	v_fmamk_f32 v142, v33, 0xbb000000, v130
	v_fmamk_f32 v128, v33, 0xbb000000, v128
	v_mul_f32_e32 v33, v129, v129
	v_mul_f32_e32 v34, v143, v143
	v_pk_mul_f32 v[130:131], v[134:135], v[134:135]
	v_pk_mul_f32 v[132:133], v[144:145], v[144:145]
	v_fmac_f32_e32 v33, v128, v128
	v_fmac_f32_e32 v34, v142, v142
	v_mov_b32_e32 v148, v130
	v_mov_b32_e32 v149, v132
	v_mov_b32_e32 v132, v131
	v_add_f32_e32 v33, v33, v34
	v_pk_add_f32 v[130:131], v[148:149], v[132:133]
	v_mov_b32_e32 v34, v139
	v_add_f32_e32 v33, v131, v33
	v_add_f32_e32 v33, v130, v33
	ds_bpermute_b32 v130, v101, v33
	v_pk_mul_f32 v[34:35], v[34:35], v[146:147]
	v_bfe_u32 v133, v65, 16, 1
	v_bfe_u32 v131, v35, 16, 1
	v_bfe_u32 v132, v34, 16, 1
	s_waitcnt lgkmcnt(0)
	v_add_f32_e32 v33, v33, v130
	ds_bpermute_b32 v130, v102, v33
	v_add3_u32 v65, v65, v133, s52
	v_add3_u32 v34, v34, v132, s52
	v_add3_u32 v35, v35, v131, s52
	v_bfe_u32 v131, v140, 16, 1
	s_waitcnt lgkmcnt(0)
	v_add_f32_e32 v33, v33, v130
	ds_bpermute_b32 v130, v103, v33
	v_bfe_u32 v132, v141, 16, 1
	v_bfe_u32 v133, v136, 16, 1
	v_add3_u32 v133, v136, v133, s52
	v_add3_u32 v132, v141, v132, s52
	s_waitcnt lgkmcnt(0)
	v_add_f32_e32 v33, v33, v130
	ds_bpermute_b32 v130, v104, v33
	v_add3_u32 v131, v140, v131, s52
	v_bfe_u32 v138, v64, 16, 1
	v_lshrrev_b32_e32 v136, 16, v131
	v_lshrrev_b32_e32 v131, 16, v132
	s_waitcnt lgkmcnt(0)
	v_add_f32_e32 v33, v33, v130
	ds_bpermute_b32 v130, v105, v33
	v_lshrrev_b32_e32 v132, 16, v133
	v_add3_u32 v64, v64, v138, s52
	v_bfe_u32 v138, v137, 16, 1
	v_and_or_b32 v132, v34, s53, v132
	s_waitcnt lgkmcnt(0)
	v_add_f32_e32 v33, v33, v130
	ds_bpermute_b32 v130, v106, v33
	v_add3_u32 v137, v137, v138, s52
	v_lshrrev_b32_e32 v133, 16, v137
	v_and_or_b32 v131, v65, s53, v131
	v_and_or_b32 v133, v35, s53, v133
	s_waitcnt lgkmcnt(0)
	v_add_f32_e32 v33, v33, v130
	v_fmamk_f32 v33, v33, 0x3b000000, v123
	v_mul_f32_e32 v34, 0x4f800000, v33
	v_cmp_gt_f32_e32 vcc, s45, v33
	v_and_or_b32 v130, v64, s53, v136
	s_nop 0
	v_cndmask_b32_e32 v33, v33, v34, vcc
	v_sqrt_f32_e32 v137, v33
	v_lshl_add_u64 v[34:35], s[40:41], 0, v[56:57]
	v_lshlrev_b64 v[34:35], 11, v[34:35]
	v_lshl_add_u64 v[34:35], v[62:63], 0, v[34:35]
	v_add_u32_e32 v64, -1, v137
	v_fma_f32 v65, -v64, v137, v33
	v_cmp_ge_f32_e64 s[0:1], 0, v65
	v_add_u32_e32 v65, 1, v137
	v_fma_f32 v136, -v65, v137, v33
	v_cndmask_b32_e64 v64, v137, v64, s[0:1]
	v_cmp_lt_f32_e64 s[0:1], 0, v136
	global_store_dwordx4 v[34:35], v[130:133], off offset:1024
	s_nop 0
	v_cndmask_b32_e64 v64, v64, v65, s[0:1]
	v_mul_f32_e32 v65, 0x37800000, v64
	v_cndmask_b32_e32 v64, v64, v65, vcc
	v_cmp_class_f32_e32 vcc, v33, v124
	s_nop 1
	v_cndmask_b32_e32 v33, v64, v33, vcc
	v_div_scale_f32 v64, s[0:1], v33, v33, 1.0
	v_rcp_f32_e32 v65, v64
	s_nop 0
	v_fma_f32 v34, -v64, v65, 1.0
	v_fmac_f32_e32 v65, v34, v65
	v_div_scale_f32 v34, vcc, 1.0, v33, 1.0
	v_mul_f32_e32 v35, v34, v65
	v_fma_f32 v130, -v64, v35, v34
	v_fmac_f32_e32 v35, v130, v65
	v_fma_f32 v34, -v64, v35, v34
	v_div_fmas_f32 v34, v34, v65, v35
	v_div_fixup_f32 v34, v34, v33, 1.0
	v_pk_mul_f32 v[64:65], v[128:129], v[34:35] op_sel_hi:[1,0]
	v_pk_mul_f32 v[128:129], v[142:143], v[34:35] op_sel_hi:[1,0]
	v_pk_fma_f32 v[64:65], v[8:9], v[64:65], v[12:13]
	v_pk_fma_f32 v[136:137], v[10:11], v[128:129], v[14:15]
	v_pk_mul_f32 v[128:129], v[144:145], v[34:35] op_sel_hi:[1,0]
	v_mul_f32_e32 v33, 0xbfb8aa3b, v64
	v_pk_fma_f32 v[138:139], v[0:1], v[128:129], v[4:5]
	v_exp_f32_e32 v33, v33
	v_mul_f32_e32 v128, 0xbfb8aa3b, v138
	v_exp_f32_e32 v128, v128
	v_pk_mul_f32 v[34:35], v[134:135], v[34:35] op_sel_hi:[1,0]
	v_add_f32_e32 v33, 1.0, v33
	v_rcp_f32_e32 v140, v33
	v_add_f32_e32 v33, 1.0, v128
	v_mul_f32_e32 v128, 0xbfb8aa3b, v65
	v_exp_f32_e32 v128, v128
	v_rcp_f32_e32 v142, v33
	v_mul_f32_e32 v33, 0xbfb8aa3b, v139
	v_exp_f32_e32 v33, v33
	v_add_f32_e32 v132, 1.0, v128
	ds_read_b128 v[128:131], v127
	v_rcp_f32_e32 v144, v132
	ds_read_b128 v[132:135], v127 offset:16
	v_add_f32_e32 v33, 1.0, v33
	v_rcp_f32_e32 v146, v33
	s_waitcnt lgkmcnt(1)
	v_mov_b32_e32 v148, v129
	v_mov_b32_e32 v149, v130
	v_mov_b32_e32 v150, v128
	v_mov_b32_e32 v151, v131
	v_pk_add_f32 v[148:149], v[148:149], v[150:151]
	s_waitcnt lgkmcnt(0)
	v_mov_b32_e32 v150, v134
	v_mov_b32_e32 v151, v132
	v_mov_b32_e32 v152, v135
	v_mov_b32_e32 v153, v133
	v_pk_add_f32 v[150:151], v[150:151], v[152:153]
	v_add_f32_e32 v33, v148, v149
	v_add_f32_e32 v33, v33, v151
	v_add_f32_e32 v33, v150, v33
	ds_bpermute_b32 v141, v101, v33
	v_pk_fma_f32 v[34:35], v[2:3], v[34:35], v[6:7]
	v_mul_f32_e32 v143, 0xbfb8aa3b, v136
	v_mul_f32_e32 v145, 0xbfb8aa3b, v34
	v_exp_f32_e32 v143, v143
	s_waitcnt lgkmcnt(0)
	v_add_f32_e32 v33, v33, v141
	ds_bpermute_b32 v147, v102, v33
	v_exp_f32_e32 v145, v145
	v_add_f32_e32 v141, 1.0, v143
	v_mul_f32_e32 v148, 0xbfb8aa3b, v35
	v_exp_f32_e32 v148, v148
	s_waitcnt lgkmcnt(0)
	v_add_f32_e32 v33, v33, v147
	v_add_f32_e32 v143, 1.0, v145
	ds_bpermute_b32 v145, v103, v33
	v_mul_f32_e32 v147, 0xbfb8aa3b, v137
	v_exp_f32_e32 v147, v147
	v_rcp_f32_e32 v141, v141
	v_rcp_f32_e32 v143, v143
	s_waitcnt lgkmcnt(0)
	v_add_f32_e32 v33, v33, v145
	ds_bpermute_b32 v149, v104, v33
	v_add_f32_e32 v145, 1.0, v147
	v_add_f32_e32 v147, 1.0, v148
	v_mov_b32_e32 v148, v64
	v_rcp_f32_e32 v145, v145
	s_waitcnt lgkmcnt(0)
	v_add_f32_e32 v33, v33, v149
	ds_bpermute_b32 v150, v105, v33
	v_mov_b32_e32 v149, v136
	v_pk_mul_f32 v[140:141], v[148:149], v[140:141]
	v_mov_b32_e32 v136, v65
	v_pk_mul_f32 v[64:65], v[136:137], v[144:145]
	s_waitcnt lgkmcnt(0)
	v_add_f32_e32 v33, v33, v150
	ds_bpermute_b32 v148, v106, v33
	v_mov_b32_e32 v136, v138
	v_mov_b32_e32 v137, v34
	v_pk_mul_f32 v[136:137], v[136:137], v[142:143]
	v_rcp_f32_e32 v147, v147
	s_waitcnt lgkmcnt(0)
	v_add_f32_e32 v33, v33, v148
	v_fmamk_f32 v143, v33, 0xbb000000, v131
	v_fmac_f32_e32 v129, 0xbb000000, v33
	v_fmamk_f32 v145, v33, 0xbb000000, v133
	v_fmamk_f32 v144, v33, 0xbb000000, v132
	v_fmamk_f32 v135, v33, 0xbb000000, v135
	v_fmac_f32_e32 v134, 0xbb000000, v33
	v_fmamk_f32 v142, v33, 0xbb000000, v130
	v_fmamk_f32 v128, v33, 0xbb000000, v128
	v_mul_f32_e32 v33, v129, v129
	v_mul_f32_e32 v34, v143, v143
	v_pk_mul_f32 v[130:131], v[134:135], v[134:135]
	v_pk_mul_f32 v[132:133], v[144:145], v[144:145]
	v_fmac_f32_e32 v33, v128, v128
	v_fmac_f32_e32 v34, v142, v142
	v_mov_b32_e32 v148, v130
	v_mov_b32_e32 v149, v132
	v_mov_b32_e32 v132, v131
	v_add_f32_e32 v33, v33, v34
	v_pk_add_f32 v[130:131], v[148:149], v[132:133]
	v_mov_b32_e32 v34, v139
	v_add_f32_e32 v33, v131, v33
	v_add_f32_e32 v33, v130, v33
	ds_bpermute_b32 v130, v101, v33
	v_pk_mul_f32 v[34:35], v[34:35], v[146:147]
	v_bfe_u32 v133, v65, 16, 1
	v_bfe_u32 v131, v35, 16, 1
	v_bfe_u32 v132, v34, 16, 1
	s_waitcnt lgkmcnt(0)
	v_add_f32_e32 v33, v33, v130
	ds_bpermute_b32 v130, v102, v33
	v_add3_u32 v65, v65, v133, s52
	v_add3_u32 v34, v34, v132, s52
	v_add3_u32 v35, v35, v131, s52
	v_bfe_u32 v131, v140, 16, 1
	s_waitcnt lgkmcnt(0)
	v_add_f32_e32 v33, v33, v130
	ds_bpermute_b32 v130, v103, v33
	v_bfe_u32 v132, v141, 16, 1
	v_bfe_u32 v133, v136, 16, 1
	v_add3_u32 v133, v136, v133, s52
	v_add3_u32 v132, v141, v132, s52
	s_waitcnt lgkmcnt(0)
	v_add_f32_e32 v33, v33, v130
	ds_bpermute_b32 v130, v104, v33
	v_add3_u32 v131, v140, v131, s52
	v_bfe_u32 v138, v64, 16, 1
	v_lshrrev_b32_e32 v136, 16, v131
	v_lshrrev_b32_e32 v131, 16, v132
	s_waitcnt lgkmcnt(0)
	v_add_f32_e32 v33, v33, v130
	ds_bpermute_b32 v130, v105, v33
	v_lshrrev_b32_e32 v132, 16, v133
	v_add3_u32 v64, v64, v138, s52
	v_bfe_u32 v138, v137, 16, 1
	v_and_or_b32 v132, v34, s53, v132
	s_waitcnt lgkmcnt(0)
	v_add_f32_e32 v33, v33, v130
	ds_bpermute_b32 v130, v106, v33
	v_add3_u32 v137, v137, v138, s52
	v_lshrrev_b32_e32 v133, 16, v137
	v_and_or_b32 v131, v65, s53, v131
	v_and_or_b32 v133, v35, s53, v133
	s_waitcnt lgkmcnt(0)
	v_add_f32_e32 v33, v33, v130
	v_fmamk_f32 v33, v33, 0x3b000000, v123
	v_mul_f32_e32 v34, 0x4f800000, v33
	v_cmp_gt_f32_e32 vcc, s45, v33
	v_and_or_b32 v130, v64, s53, v136
	s_nop 0
	v_cndmask_b32_e32 v33, v33, v34, vcc
	v_sqrt_f32_e32 v137, v33
	v_lshl_add_u64 v[34:35], s[40:41], 0, v[58:59]
	v_lshlrev_b64 v[34:35], 11, v[34:35]
	v_lshl_add_u64 v[34:35], v[62:63], 0, v[34:35]
	v_add_u32_e32 v64, -1, v137
	v_fma_f32 v65, -v64, v137, v33
	v_cmp_ge_f32_e64 s[0:1], 0, v65
	v_add_u32_e32 v65, 1, v137
	v_fma_f32 v136, -v65, v137, v33
	v_cndmask_b32_e64 v64, v137, v64, s[0:1]
	v_cmp_lt_f32_e64 s[0:1], 0, v136
	global_store_dwordx4 v[34:35], v[130:133], off offset:1024
	s_nop 0
	v_cndmask_b32_e64 v64, v64, v65, s[0:1]
	v_mul_f32_e32 v65, 0x37800000, v64
	v_cndmask_b32_e32 v64, v64, v65, vcc
	v_cmp_class_f32_e32 vcc, v33, v124
	s_nop 1
	v_cndmask_b32_e32 v33, v64, v33, vcc
	v_div_scale_f32 v64, s[0:1], v33, v33, 1.0
	v_rcp_f32_e32 v65, v64
	s_nop 0
	v_fma_f32 v34, -v64, v65, 1.0
	v_fmac_f32_e32 v65, v34, v65
	v_div_scale_f32 v34, vcc, 1.0, v33, 1.0
	v_mul_f32_e32 v35, v34, v65
	v_fma_f32 v130, -v64, v35, v34
	v_fmac_f32_e32 v35, v130, v65
	v_fma_f32 v34, -v64, v35, v34
	v_div_fmas_f32 v34, v34, v65, v35
	v_div_fixup_f32 v34, v34, v33, 1.0
	v_pk_mul_f32 v[64:65], v[128:129], v[34:35] op_sel_hi:[1,0]
	v_pk_mul_f32 v[130:131], v[144:145], v[34:35] op_sel_hi:[1,0]
	v_pk_fma_f32 v[64:65], v[8:9], v[64:65], v[12:13]
	v_pk_fma_f32 v[130:131], v[0:1], v[130:131], v[4:5]
	v_mul_f32_e32 v33, 0xbfb8aa3b, v64
	v_exp_f32_e32 v33, v33
	v_mul_f32_e32 v132, 0xbfb8aa3b, v130
	v_exp_f32_e32 v133, v132
	v_pk_mul_f32 v[128:129], v[142:143], v[34:35] op_sel_hi:[1,0]
	v_add_f32_e32 v33, 1.0, v33
	v_rcp_f32_e32 v132, v33
	v_add_f32_e32 v33, 1.0, v133
	v_mul_f32_e32 v133, 0xbfb8aa3b, v65
	v_pk_mul_f32 v[34:35], v[134:135], v[34:35] op_sel_hi:[1,0]
	v_exp_f32_e32 v133, v133
	v_mul_f32_e32 v134, 0xbfb8aa3b, v131
	v_exp_f32_e32 v135, v134
	v_pk_fma_f32 v[128:129], v[10:11], v[128:129], v[14:15]
	v_pk_fma_f32 v[34:35], v[2:3], v[34:35], v[6:7]
	v_rcp_f32_e32 v134, v33
	v_add_f32_e32 v33, 1.0, v133
	v_mul_f32_e32 v133, 0xbfb8aa3b, v128
	v_rcp_f32_e32 v136, v33
	v_add_f32_e32 v33, 1.0, v135
	v_exp_f32_e32 v133, v133
	v_mul_f32_e32 v135, 0xbfb8aa3b, v34
	v_exp_f32_e32 v135, v135
	v_rcp_f32_e32 v138, v33
	v_add_f32_e32 v33, 1.0, v133
	v_rcp_f32_e32 v133, v33
	v_add_f32_e32 v33, 1.0, v135
	v_mul_f32_e32 v135, 0xbfb8aa3b, v129
	v_exp_f32_e32 v137, v135
	v_mul_f32_e32 v135, 0xbfb8aa3b, v35
	v_exp_f32_e32 v139, v135
	v_rcp_f32_e32 v135, v33
	v_add_f32_e32 v33, 1.0, v137
	v_rcp_f32_e32 v137, v33
	v_add_f32_e32 v33, 1.0, v139
	v_rcp_f32_e32 v139, v33
	v_mov_b32_e32 v141, v128
	v_mov_b32_e32 v128, v65
	v_mov_b32_e32 v140, v64
	v_pk_mul_f32 v[64:65], v[128:129], v[136:137]
	v_mov_b32_e32 v129, v34
	v_mov_b32_e32 v34, v131
	v_mov_b32_e32 v128, v130
	v_pk_mul_f32 v[34:35], v[34:35], v[138:139]
	v_pk_mul_f32 v[132:133], v[140:141], v[132:133]
	v_pk_mul_f32 v[128:129], v[128:129], v[134:135]
	v_bfe_u32 v33, v35, 16, 1
	v_bfe_u32 v131, v65, 16, 1
	v_bfe_u32 v130, v34, 16, 1
	v_add3_u32 v65, v65, v131, s52
	v_add3_u32 v33, v35, v33, s52
	v_bfe_u32 v35, v132, 16, 1
	v_bfe_u32 v131, v128, 16, 1
	v_bfe_u32 v134, v64, 16, 1
	v_add3_u32 v34, v34, v130, s52
	v_bfe_u32 v130, v133, 16, 1
	v_add3_u32 v128, v128, v131, s52
	v_add3_u32 v35, v132, v35, s52
	v_add3_u32 v64, v64, v134, s52
	v_bfe_u32 v134, v129, 16, 1
	v_add3_u32 v130, v133, v130, s52
	v_lshrrev_b32_e32 v35, 16, v35
	v_lshrrev_b32_e32 v128, 16, v128
	v_add3_u32 v129, v129, v134, s52
	v_lshrrev_b32_e32 v132, 16, v130
	v_and_or_b32 v130, v34, s53, v128
	v_and_or_b32 v128, v64, s53, v35
	v_lshl_add_u64 v[34:35], s[40:41], 0, v[60:61]
	v_lshrrev_b32_e32 v129, 16, v129
	v_lshlrev_b64 v[34:35], 11, v[34:35]
	v_and_or_b32 v131, v33, s53, v129
	v_and_or_b32 v129, v65, s53, v132
	v_lshl_add_u64 v[34:35], v[62:63], 0, v[34:35]
	global_store_dwordx4 v[34:35], v[128:131], off offset:1024
	s_cbranch_scc0 .LBB0_484
